# GEMM epilogue stores write-through (sc1) so the grid-barrier L2 writeback has less to flush
# baseline (speedup 1.0000x reference)
.LBB0_39:
	s_waitcnt vmcnt(0)
	v_pk_add_f32 v[132:133], v[128:129], v[132:133]
	v_pk_add_f32 v[146:147], v[126:127], v[130:131]
	v_pk_add_f32 v[136:137], v[124:125], v[136:137]
	v_pk_add_f32 v[134:135], v[122:123], v[134:135]
	s_and_b64 vcc, exec, s[44:45]
	v_cvt_pk_bf16_f32 v122, v146, v147
	v_cvt_pk_bf16_f32 v123, v132, v133
	v_cvt_pk_bf16_f32 v124, v134, v135
	v_cvt_pk_bf16_f32 v125, v136, v137
	global_store_dwordx4 v[148:149], v[122:125], off sc1
	s_cbranch_vccnz .LBB0_104
	global_load_dwordx4 v[126:129], v[144:145], off offset:528
	global_load_dwordx4 v[122:125], v[144:145], off offset:512
	v_or_b32_e32 v142, 0x80, v142
	v_lshl_add_u64 v[130:131], v[142:143], 1, s[14:15]
	s_cbranch_execnz .LBB0_42

.LBB0_42:
	s_waitcnt vmcnt(0)
	v_pk_add_f32 v[120:121], v[120:121], v[124:125]
	v_pk_add_f32 v[118:119], v[118:119], v[122:123]
	v_pk_add_f32 v[124:125], v[114:115], v[126:127]
	v_mul_f32_e32 v114, v119, v119
	v_mul_f32_e32 v115, v121, v121
	v_mul_f32_e32 v142, v147, v147
	v_mul_f32_e32 v133, v133, v133
	v_pk_add_f32 v[122:123], v[116:117], v[128:129]
	v_fmac_f32_e32 v114, v118, v118
	v_fmac_f32_e32 v115, v120, v120
	v_fmac_f32_e32 v142, v146, v146
	v_fmac_f32_e32 v133, v132, v132
	v_add_f32_e32 v114, v114, v115
	v_mul_f32_e32 v115, v125, v125
	v_mul_f32_e32 v116, v123, v123
	v_add_f32_e32 v132, v142, v133
	v_mul_f32_e32 v133, v135, v135
	v_fmac_f32_e32 v115, v124, v124
	v_fmac_f32_e32 v116, v122, v122
	v_fmac_f32_e32 v133, v134, v134
	v_mul_f32_e32 v134, v137, v137
	v_add_f32_e32 v115, v115, v116
	v_and_b32_e32 v116, 64, v222
	v_fmac_f32_e32 v134, v136, v136
	v_add_f32_e32 v114, v114, v115
	v_xor_b32_e32 v115, 16, v222
	v_add_u32_e32 v117, 64, v116
	v_add_f32_e32 v133, v133, v134
	v_cmp_lt_i32_e32 vcc, v115, v117
	v_add_f32_e32 v132, v132, v133
	v_add_f32_e32 v114, v132, v114
	v_cndmask_b32_e32 v115, v222, v115, vcc
	v_lshlrev_b32_e32 v132, 2, v115
	ds_bpermute_b32 v115, v132, v114
	s_lshl_b32 s96, s84, 2
	s_ashr_i32 s97, s96, 31
	v_cvt_pk_bf16_f32 v116, v118, v119
	s_waitcnt lgkmcnt(0)
	v_add_f32_e32 v114, v114, v115
	v_xor_b32_e32 v115, 32, v222
	v_cmp_lt_i32_e32 vcc, v115, v117
	v_cvt_pk_bf16_f32 v117, v120, v121
	v_cvt_pk_bf16_f32 v118, v124, v125
	v_cvt_pk_bf16_f32 v119, v122, v123
	global_store_dwordx4 v[130:131], v[116:119], off sc1
	s_nop 0
	v_cndmask_b32_e32 v115, v222, v115, vcc
	v_lshlrev_b32_e32 v133, 2, v115
	ds_bpermute_b32 v115, v133, v114
	s_and_saveexec_b64 s[26:27], s[40:41]
	s_cbranch_execz .LBB0_44
	v_readlane_b32 s48, v252, 13
	v_lshlrev_b64 v[116:117], 6, v[140:141]
	v_readlane_b32 s49, v252, 14
	s_lshl_b32 s84, s28, 2
	s_waitcnt lgkmcnt(0)
	v_add_f32_e32 v114, v114, v115
	v_lshl_add_u64 v[116:117], s[48:49], 0, v[116:117]
	v_lshl_add_u64 v[116:117], s[96:97], 2, v[116:117]
	v_lshl_add_u64 v[116:117], v[116:117], 0, s[84:85]
	global_store_dword v[116:117], v114, off

.LBB0_47:
	s_waitcnt vmcnt(0)
	v_pk_add_f32 v[116:117], v[112:113], v[116:117]
	v_pk_add_f32 v[128:129], v[110:111], v[114:115]
	v_pk_add_f32 v[120:121], v[108:109], v[120:121]
	v_pk_add_f32 v[118:119], v[106:107], v[118:119]
	s_and_b64 vcc, exec, s[44:45]
	v_cvt_pk_bf16_f32 v106, v128, v129
	v_cvt_pk_bf16_f32 v107, v116, v117
	v_cvt_pk_bf16_f32 v108, v118, v119
	v_cvt_pk_bf16_f32 v109, v120, v121
	global_store_dwordx4 v[130:131], v[106:109], off sc1
	s_cbranch_vccnz .LBB0_106
	global_load_dwordx4 v[110:113], v[126:127], off offset:528
	global_load_dwordx4 v[106:109], v[126:127], off offset:512
	v_or_b32_e32 v124, 0x80, v124
	v_lshl_add_u64 v[114:115], v[124:125], 1, s[14:15]
	s_cbranch_execnz .LBB0_50

.LBB0_50:
	v_mul_f32_e32 v124, v129, v129
	v_mul_f32_e32 v117, v117, v117
	s_waitcnt vmcnt(0)
	v_pk_add_f32 v[104:105], v[104:105], v[108:109]
	v_pk_add_f32 v[102:103], v[102:103], v[106:107]
	v_fmac_f32_e32 v124, v128, v128
	v_fmac_f32_e32 v117, v116, v116
	v_pk_add_f32 v[108:109], v[98:99], v[110:111]
	v_mul_f32_e32 v98, v103, v103
	v_mul_f32_e32 v99, v105, v105
	v_add_f32_e32 v116, v124, v117
	v_mul_f32_e32 v117, v119, v119
	v_pk_add_f32 v[106:107], v[100:101], v[112:113]
	v_fmac_f32_e32 v98, v102, v102
	v_fmac_f32_e32 v99, v104, v104
	v_fmac_f32_e32 v117, v118, v118
	v_mul_f32_e32 v118, v121, v121
	v_add_f32_e32 v98, v98, v99
	v_mul_f32_e32 v99, v109, v109
	v_mul_f32_e32 v100, v107, v107
	v_fmac_f32_e32 v118, v120, v120
	v_fmac_f32_e32 v99, v108, v108
	v_fmac_f32_e32 v100, v106, v106
	v_add_f32_e32 v117, v117, v118
	v_add_f32_e32 v99, v99, v100
	v_add_f32_e32 v116, v116, v117
	v_add_f32_e32 v98, v98, v99
	v_add_f32_e32 v98, v116, v98
	ds_bpermute_b32 v99, v132, v98
	v_cvt_pk_bf16_f32 v100, v102, v103
	v_cvt_pk_bf16_f32 v101, v104, v105
	v_cvt_pk_bf16_f32 v102, v108, v109
	v_cvt_pk_bf16_f32 v103, v106, v107
	s_waitcnt lgkmcnt(0)
	v_add_f32_e32 v98, v98, v99
	ds_bpermute_b32 v99, v133, v98
	global_store_dwordx4 v[114:115], v[100:103], off sc1
	s_and_saveexec_b64 s[26:27], s[40:41]
	s_cbranch_execz .LBB0_52
	v_readlane_b32 s48, v252, 13
	v_lshlrev_b64 v[100:101], 6, v[122:123]
	v_readlane_b32 s49, v252, 14
	s_lshl_b32 s84, s28, 2
	s_waitcnt lgkmcnt(0)
	v_add_f32_e32 v98, v98, v99
	v_lshl_add_u64 v[100:101], s[48:49], 0, v[100:101]
	v_lshl_add_u64 v[100:101], s[96:97], 2, v[100:101]
	v_lshl_add_u64 v[100:101], v[100:101], 0, s[84:85]
	global_store_dword v[100:101], v98, off

.LBB0_55:
	s_waitcnt vmcnt(0)
	v_pk_add_f32 v[100:101], v[96:97], v[100:101]
	v_pk_add_f32 v[112:113], v[94:95], v[98:99]
	v_pk_add_f32 v[104:105], v[92:93], v[104:105]
	v_pk_add_f32 v[102:103], v[90:91], v[102:103]
	s_and_b64 vcc, exec, s[44:45]
	v_cvt_pk_bf16_f32 v90, v112, v113
	v_cvt_pk_bf16_f32 v91, v100, v101
	v_cvt_pk_bf16_f32 v92, v102, v103
	v_cvt_pk_bf16_f32 v93, v104, v105
	global_store_dwordx4 v[114:115], v[90:93], off sc1
	s_cbranch_vccnz .LBB0_108
	global_load_dwordx4 v[94:97], v[110:111], off offset:528
	global_load_dwordx4 v[90:93], v[110:111], off offset:512
	v_or_b32_e32 v108, 0x80, v108
	v_lshl_add_u64 v[98:99], v[108:109], 1, s[14:15]
	s_cbranch_execnz .LBB0_58

.LBB0_58:
	v_mul_f32_e32 v108, v113, v113
	v_mul_f32_e32 v101, v101, v101
	s_waitcnt vmcnt(0)
	v_pk_add_f32 v[88:89], v[88:89], v[92:93]
	v_pk_add_f32 v[86:87], v[86:87], v[90:91]
	v_fmac_f32_e32 v108, v112, v112
	v_fmac_f32_e32 v101, v100, v100
	v_pk_add_f32 v[92:93], v[82:83], v[94:95]
	v_mul_f32_e32 v82, v87, v87
	v_mul_f32_e32 v83, v89, v89
	v_add_f32_e32 v100, v108, v101
	v_mul_f32_e32 v101, v103, v103
	v_pk_add_f32 v[90:91], v[84:85], v[96:97]
	v_fmac_f32_e32 v82, v86, v86
	v_fmac_f32_e32 v83, v88, v88
	v_fmac_f32_e32 v101, v102, v102
	v_mul_f32_e32 v102, v105, v105
	v_add_f32_e32 v82, v82, v83
	v_mul_f32_e32 v83, v93, v93
	v_mul_f32_e32 v84, v91, v91
	v_fmac_f32_e32 v102, v104, v104
	v_fmac_f32_e32 v83, v92, v92
	v_fmac_f32_e32 v84, v90, v90
	v_add_f32_e32 v101, v101, v102
	v_add_f32_e32 v83, v83, v84
	v_add_f32_e32 v100, v100, v101
	v_add_f32_e32 v82, v82, v83
	v_add_f32_e32 v82, v100, v82
	ds_bpermute_b32 v83, v132, v82
	v_cvt_pk_bf16_f32 v84, v86, v87
	v_cvt_pk_bf16_f32 v85, v88, v89
	v_cvt_pk_bf16_f32 v86, v92, v93
	v_cvt_pk_bf16_f32 v87, v90, v91
	s_waitcnt lgkmcnt(0)
	v_add_f32_e32 v82, v82, v83
	ds_bpermute_b32 v83, v133, v82
	global_store_dwordx4 v[98:99], v[84:87], off sc1
	s_and_saveexec_b64 s[26:27], s[40:41]
	s_cbranch_execz .LBB0_60
	v_readlane_b32 s48, v252, 13
	v_lshlrev_b64 v[84:85], 6, v[106:107]
	v_readlane_b32 s49, v252, 14
	s_lshl_b32 s84, s28, 2
	s_waitcnt lgkmcnt(0)
	v_add_f32_e32 v82, v82, v83
	v_lshl_add_u64 v[84:85], s[48:49], 0, v[84:85]
	v_lshl_add_u64 v[84:85], s[96:97], 2, v[84:85]
	v_lshl_add_u64 v[84:85], v[84:85], 0, s[84:85]
	global_store_dword v[84:85], v82, off

.LBB0_63:
	s_waitcnt vmcnt(0)
	v_pk_add_f32 v[84:85], v[80:81], v[84:85]
	v_pk_add_f32 v[96:97], v[78:79], v[82:83]
	v_pk_add_f32 v[88:89], v[76:77], v[88:89]
	v_pk_add_f32 v[86:87], v[74:75], v[86:87]
	s_and_b64 vcc, exec, s[44:45]
	v_cvt_pk_bf16_f32 v74, v96, v97
	v_cvt_pk_bf16_f32 v75, v84, v85
	v_cvt_pk_bf16_f32 v76, v86, v87
	v_cvt_pk_bf16_f32 v77, v88, v89
	global_store_dwordx4 v[98:99], v[74:77], off sc1
	s_cbranch_vccnz .LBB0_110
	global_load_dwordx4 v[78:81], v[94:95], off offset:528
	global_load_dwordx4 v[74:77], v[94:95], off offset:512
	v_or_b32_e32 v92, 0x80, v92
	v_lshl_add_u64 v[82:83], v[92:93], 1, s[14:15]
	s_cbranch_execnz .LBB0_66

.LBB0_66:
	v_mul_f32_e32 v92, v97, v97
	v_mul_f32_e32 v85, v85, v85
	s_waitcnt vmcnt(0)
	v_pk_add_f32 v[72:73], v[72:73], v[76:77]
	v_pk_add_f32 v[70:71], v[70:71], v[74:75]
	v_fmac_f32_e32 v92, v96, v96
	v_fmac_f32_e32 v85, v84, v84
	v_pk_add_f32 v[76:77], v[66:67], v[78:79]
	v_mul_f32_e32 v66, v71, v71
	v_mul_f32_e32 v67, v73, v73
	v_add_f32_e32 v84, v92, v85
	v_mul_f32_e32 v85, v87, v87
	v_pk_add_f32 v[74:75], v[68:69], v[80:81]
	v_fmac_f32_e32 v66, v70, v70
	v_fmac_f32_e32 v67, v72, v72
	v_fmac_f32_e32 v85, v86, v86
	v_mul_f32_e32 v86, v89, v89
	v_add_f32_e32 v66, v66, v67
	v_mul_f32_e32 v67, v77, v77
	v_mul_f32_e32 v68, v75, v75
	v_fmac_f32_e32 v86, v88, v88
	v_fmac_f32_e32 v67, v76, v76
	v_fmac_f32_e32 v68, v74, v74
	v_add_f32_e32 v85, v85, v86
	v_add_f32_e32 v67, v67, v68
	v_add_f32_e32 v84, v84, v85
	v_add_f32_e32 v66, v66, v67
	v_add_f32_e32 v66, v84, v66
	ds_bpermute_b32 v67, v132, v66
	v_cvt_pk_bf16_f32 v68, v70, v71
	v_cvt_pk_bf16_f32 v69, v72, v73
	v_cvt_pk_bf16_f32 v70, v76, v77
	v_cvt_pk_bf16_f32 v71, v74, v75
	s_waitcnt lgkmcnt(0)
	v_add_f32_e32 v66, v66, v67
	ds_bpermute_b32 v67, v133, v66
	global_store_dwordx4 v[82:83], v[68:71], off sc1
	s_and_saveexec_b64 s[26:27], s[40:41]
	s_cbranch_execz .LBB0_68
	v_readlane_b32 s48, v252, 13
	v_lshlrev_b64 v[68:69], 6, v[90:91]
	v_readlane_b32 s49, v252, 14
	s_lshl_b32 s84, s28, 2
	s_waitcnt lgkmcnt(0)
	v_add_f32_e32 v66, v66, v67
	v_lshl_add_u64 v[68:69], s[48:49], 0, v[68:69]
	v_lshl_add_u64 v[68:69], s[96:97], 2, v[68:69]
	v_lshl_add_u64 v[68:69], v[68:69], 0, s[84:85]
	global_store_dword v[68:69], v66, off

.LBB0_71:
	s_waitcnt vmcnt(0)
	v_pk_add_f32 v[68:69], v[64:65], v[68:69]
	v_pk_add_f32 v[80:81], v[62:63], v[66:67]
	v_pk_add_f32 v[72:73], v[60:61], v[72:73]
	v_pk_add_f32 v[70:71], v[58:59], v[70:71]
	s_and_b64 vcc, exec, s[44:45]
	v_cvt_pk_bf16_f32 v58, v80, v81
	v_cvt_pk_bf16_f32 v59, v68, v69
	v_cvt_pk_bf16_f32 v60, v70, v71
	v_cvt_pk_bf16_f32 v61, v72, v73
	global_store_dwordx4 v[82:83], v[58:61], off sc1
	s_cbranch_vccnz .LBB0_112
	global_load_dwordx4 v[62:65], v[78:79], off offset:528
	global_load_dwordx4 v[58:61], v[78:79], off offset:512
	v_or_b32_e32 v76, 0x80, v76
	v_lshl_add_u64 v[66:67], v[76:77], 1, s[14:15]
	s_cbranch_execnz .LBB0_74

.LBB0_74:
	v_mul_f32_e32 v76, v81, v81
	v_mul_f32_e32 v69, v69, v69
	s_waitcnt vmcnt(0)
	v_pk_add_f32 v[56:57], v[56:57], v[60:61]
	v_pk_add_f32 v[54:55], v[54:55], v[58:59]
	v_fmac_f32_e32 v76, v80, v80
	v_fmac_f32_e32 v69, v68, v68
	v_pk_add_f32 v[60:61], v[50:51], v[62:63]
	v_mul_f32_e32 v50, v55, v55
	v_mul_f32_e32 v51, v57, v57
	v_add_f32_e32 v68, v76, v69
	v_mul_f32_e32 v69, v71, v71
	v_pk_add_f32 v[58:59], v[52:53], v[64:65]
	v_fmac_f32_e32 v50, v54, v54
	v_fmac_f32_e32 v51, v56, v56
	v_fmac_f32_e32 v69, v70, v70
	v_mul_f32_e32 v70, v73, v73
	v_add_f32_e32 v50, v50, v51
	v_mul_f32_e32 v51, v61, v61
	v_mul_f32_e32 v52, v59, v59
	v_fmac_f32_e32 v70, v72, v72
	v_fmac_f32_e32 v51, v60, v60
	v_fmac_f32_e32 v52, v58, v58
	v_add_f32_e32 v69, v69, v70
	v_add_f32_e32 v51, v51, v52
	v_add_f32_e32 v68, v68, v69
	v_add_f32_e32 v50, v50, v51
	v_add_f32_e32 v50, v68, v50
	ds_bpermute_b32 v51, v132, v50
	v_cvt_pk_bf16_f32 v52, v54, v55
	v_cvt_pk_bf16_f32 v53, v56, v57
	v_cvt_pk_bf16_f32 v54, v60, v61
	v_cvt_pk_bf16_f32 v55, v58, v59
	s_waitcnt lgkmcnt(0)
	v_add_f32_e32 v50, v50, v51
	ds_bpermute_b32 v51, v133, v50
	global_store_dwordx4 v[66:67], v[52:55], off sc1
	s_and_saveexec_b64 s[26:27], s[40:41]
	s_cbranch_execz .LBB0_76
	v_readlane_b32 s48, v252, 13
	v_lshlrev_b64 v[52:53], 6, v[74:75]
	v_readlane_b32 s49, v252, 14
	s_lshl_b32 s84, s28, 2
	s_waitcnt lgkmcnt(0)
	v_add_f32_e32 v50, v50, v51
	v_lshl_add_u64 v[52:53], s[48:49], 0, v[52:53]
	v_lshl_add_u64 v[52:53], s[96:97], 2, v[52:53]
	v_lshl_add_u64 v[52:53], v[52:53], 0, s[84:85]
	global_store_dword v[52:53], v50, off

.LBB0_79:
	s_waitcnt vmcnt(0)
	v_pk_add_f32 v[52:53], v[48:49], v[52:53]
	v_pk_add_f32 v[64:65], v[46:47], v[50:51]
	v_pk_add_f32 v[56:57], v[44:45], v[56:57]
	v_pk_add_f32 v[54:55], v[42:43], v[54:55]
	s_and_b64 vcc, exec, s[44:45]
	v_cvt_pk_bf16_f32 v42, v64, v65
	v_cvt_pk_bf16_f32 v43, v52, v53
	v_cvt_pk_bf16_f32 v44, v54, v55
	v_cvt_pk_bf16_f32 v45, v56, v57
	global_store_dwordx4 v[66:67], v[42:45], off sc1
	s_cbranch_vccnz .LBB0_114
	global_load_dwordx4 v[46:49], v[62:63], off offset:528
	global_load_dwordx4 v[42:45], v[62:63], off offset:512
	v_or_b32_e32 v60, 0x80, v60
	v_lshl_add_u64 v[50:51], v[60:61], 1, s[14:15]
	s_cbranch_execnz .LBB0_82

.LBB0_82:
	v_mul_f32_e32 v60, v65, v65
	v_mul_f32_e32 v53, v53, v53
	s_waitcnt vmcnt(0)
	v_pk_add_f32 v[40:41], v[40:41], v[44:45]
	v_pk_add_f32 v[38:39], v[38:39], v[42:43]
	v_fmac_f32_e32 v60, v64, v64
	v_fmac_f32_e32 v53, v52, v52
	v_pk_add_f32 v[44:45], v[34:35], v[46:47]
	v_mul_f32_e32 v34, v39, v39
	v_mul_f32_e32 v35, v41, v41
	v_add_f32_e32 v52, v60, v53
	v_mul_f32_e32 v53, v55, v55
	v_pk_add_f32 v[42:43], v[36:37], v[48:49]
	v_fmac_f32_e32 v34, v38, v38
	v_fmac_f32_e32 v35, v40, v40
	v_fmac_f32_e32 v53, v54, v54
	v_mul_f32_e32 v54, v57, v57
	v_add_f32_e32 v34, v34, v35
	v_mul_f32_e32 v35, v45, v45
	v_mul_f32_e32 v36, v43, v43
	v_fmac_f32_e32 v54, v56, v56
	v_fmac_f32_e32 v35, v44, v44
	v_fmac_f32_e32 v36, v42, v42
	v_add_f32_e32 v53, v53, v54
	v_add_f32_e32 v35, v35, v36
	v_add_f32_e32 v52, v52, v53
	v_add_f32_e32 v34, v34, v35
	v_add_f32_e32 v34, v52, v34
	ds_bpermute_b32 v35, v132, v34
	v_cvt_pk_bf16_f32 v36, v38, v39
	v_cvt_pk_bf16_f32 v37, v40, v41
	v_cvt_pk_bf16_f32 v38, v44, v45
	v_cvt_pk_bf16_f32 v39, v42, v43
	s_waitcnt lgkmcnt(0)
	v_add_f32_e32 v34, v34, v35
	ds_bpermute_b32 v35, v133, v34
	global_store_dwordx4 v[50:51], v[36:39], off sc1
	s_and_saveexec_b64 s[26:27], s[40:41]
	s_cbranch_execz .LBB0_84
	v_readlane_b32 s48, v252, 13
	v_lshlrev_b64 v[36:37], 6, v[58:59]
	v_readlane_b32 s49, v252, 14
	s_lshl_b32 s84, s28, 2
	s_waitcnt lgkmcnt(0)
	v_add_f32_e32 v34, v34, v35
	v_lshl_add_u64 v[36:37], s[48:49], 0, v[36:37]
	v_lshl_add_u64 v[36:37], s[96:97], 2, v[36:37]
	v_lshl_add_u64 v[36:37], v[36:37], 0, s[84:85]
	global_store_dword v[36:37], v34, off

.LBB0_87:
	s_waitcnt vmcnt(0)
	v_pk_add_f32 v[36:37], v[32:33], v[36:37]
	v_pk_add_f32 v[48:49], v[30:31], v[34:35]
	v_pk_add_f32 v[40:41], v[28:29], v[40:41]
	v_pk_add_f32 v[38:39], v[26:27], v[38:39]
	s_and_b64 vcc, exec, s[44:45]
	v_cvt_pk_bf16_f32 v26, v48, v49
	v_cvt_pk_bf16_f32 v27, v36, v37
	v_cvt_pk_bf16_f32 v28, v38, v39
	v_cvt_pk_bf16_f32 v29, v40, v41
	global_store_dwordx4 v[50:51], v[26:29], off sc1
	s_cbranch_vccnz .LBB0_116
	global_load_dwordx4 v[30:33], v[46:47], off offset:528
	global_load_dwordx4 v[26:29], v[46:47], off offset:512
	v_or_b32_e32 v44, 0x80, v44
	v_lshl_add_u64 v[34:35], v[44:45], 1, s[14:15]
	s_cbranch_execnz .LBB0_90

.LBB0_90:
	v_mul_f32_e32 v44, v49, v49
	v_mul_f32_e32 v37, v37, v37
	s_waitcnt vmcnt(0)
	v_pk_add_f32 v[24:25], v[24:25], v[28:29]
	v_pk_add_f32 v[22:23], v[22:23], v[26:27]
	v_fmac_f32_e32 v44, v48, v48
	v_fmac_f32_e32 v37, v36, v36
	v_pk_add_f32 v[28:29], v[18:19], v[30:31]
	v_mul_f32_e32 v18, v23, v23
	v_mul_f32_e32 v19, v25, v25
	v_add_f32_e32 v36, v44, v37
	v_mul_f32_e32 v37, v39, v39
	v_pk_add_f32 v[26:27], v[20:21], v[32:33]
	v_fmac_f32_e32 v18, v22, v22
	v_fmac_f32_e32 v19, v24, v24
	v_fmac_f32_e32 v37, v38, v38
	v_mul_f32_e32 v38, v41, v41
	v_add_f32_e32 v18, v18, v19
	v_mul_f32_e32 v19, v29, v29
	v_mul_f32_e32 v20, v27, v27
	v_fmac_f32_e32 v38, v40, v40
	v_fmac_f32_e32 v19, v28, v28
	v_fmac_f32_e32 v20, v26, v26
	v_add_f32_e32 v37, v37, v38
	v_add_f32_e32 v19, v19, v20
	v_add_f32_e32 v36, v36, v37
	v_add_f32_e32 v18, v18, v19
	v_add_f32_e32 v18, v36, v18
	ds_bpermute_b32 v19, v132, v18
	v_cvt_pk_bf16_f32 v20, v22, v23
	v_cvt_pk_bf16_f32 v21, v24, v25
	v_cvt_pk_bf16_f32 v22, v28, v29
	v_cvt_pk_bf16_f32 v23, v26, v27
	s_waitcnt lgkmcnt(0)
	v_add_f32_e32 v18, v18, v19
	ds_bpermute_b32 v19, v133, v18
	global_store_dwordx4 v[34:35], v[20:23], off sc1
	s_and_saveexec_b64 s[26:27], s[40:41]
	s_cbranch_execz .LBB0_92
	v_readlane_b32 s48, v252, 13
	v_lshlrev_b64 v[20:21], 6, v[42:43]
	v_readlane_b32 s49, v252, 14
	s_lshl_b32 s84, s28, 2
	s_waitcnt lgkmcnt(0)
	v_add_f32_e32 v18, v18, v19
	v_lshl_add_u64 v[20:21], s[48:49], 0, v[20:21]
	v_lshl_add_u64 v[20:21], s[96:97], 2, v[20:21]
	v_lshl_add_u64 v[20:21], v[20:21], 0, s[84:85]
	global_store_dword v[20:21], v18, off

.LBB0_95:
	s_waitcnt vmcnt(0)
	v_pk_add_f32 v[20:21], v[16:17], v[20:21]
	v_pk_add_f32 v[32:33], v[14:15], v[18:19]
	v_pk_add_f32 v[24:25], v[12:13], v[24:25]
	v_pk_add_f32 v[22:23], v[10:11], v[22:23]
	s_and_b64 vcc, exec, s[44:45]
	v_cvt_pk_bf16_f32 v10, v32, v33
	v_cvt_pk_bf16_f32 v11, v20, v21
	v_cvt_pk_bf16_f32 v12, v22, v23
	v_cvt_pk_bf16_f32 v13, v24, v25
	global_store_dwordx4 v[34:35], v[10:13], off sc1
	s_cbranch_vccnz .LBB0_118
	global_load_dwordx4 v[14:17], v[30:31], off offset:528
	global_load_dwordx4 v[10:13], v[30:31], off offset:512
	v_or_b32_e32 v28, 0x80, v28
	v_lshl_add_u64 v[18:19], v[28:29], 1, s[14:15]
	s_cbranch_execnz .LBB0_98

.LBB0_98:
	v_mul_f32_e32 v28, v33, v33
	v_mul_f32_e32 v21, v21, v21
	s_waitcnt vmcnt(0)
	v_pk_add_f32 v[8:9], v[8:9], v[12:13]
	v_pk_add_f32 v[6:7], v[6:7], v[10:11]
	v_fmac_f32_e32 v28, v32, v32
	v_fmac_f32_e32 v21, v20, v20
	v_pk_add_f32 v[12:13], v[2:3], v[14:15]
	v_mul_f32_e32 v2, v7, v7
	v_mul_f32_e32 v3, v9, v9
	v_add_f32_e32 v20, v28, v21
	v_mul_f32_e32 v21, v23, v23
	v_pk_add_f32 v[10:11], v[4:5], v[16:17]
	v_fmac_f32_e32 v2, v6, v6
	v_fmac_f32_e32 v3, v8, v8
	v_fmac_f32_e32 v21, v22, v22
	v_mul_f32_e32 v22, v25, v25
	v_add_f32_e32 v2, v2, v3
	v_mul_f32_e32 v3, v13, v13
	v_mul_f32_e32 v4, v11, v11
	v_fmac_f32_e32 v22, v24, v24
	v_fmac_f32_e32 v3, v12, v12
	v_fmac_f32_e32 v4, v10, v10
	v_add_f32_e32 v21, v21, v22
	v_add_f32_e32 v3, v3, v4
	v_add_f32_e32 v20, v20, v21
	v_add_f32_e32 v2, v2, v3
	v_add_f32_e32 v2, v20, v2
	ds_bpermute_b32 v3, v132, v2
	v_cvt_pk_bf16_f32 v4, v6, v7
	v_cvt_pk_bf16_f32 v5, v8, v9
	v_cvt_pk_bf16_f32 v6, v12, v13
	v_cvt_pk_bf16_f32 v7, v10, v11
	s_waitcnt lgkmcnt(0)
	v_add_f32_e32 v2, v2, v3
	ds_bpermute_b32 v3, v133, v2
	global_store_dwordx4 v[18:19], v[4:7], off sc1
	s_and_saveexec_b64 s[26:27], s[40:41]
	s_cbranch_execz .LBB0_100
	v_readlane_b32 s44, v252, 13
	v_lshlrev_b64 v[4:5], 6, v[26:27]
	v_readlane_b32 s45, v252, 14
	s_lshl_b32 s84, s28, 2
	s_waitcnt lgkmcnt(0)
	v_add_f32_e32 v2, v2, v3
	v_lshl_add_u64 v[4:5], s[44:45], 0, v[4:5]
	v_lshl_add_u64 v[4:5], s[96:97], 2, v[4:5]
	v_lshl_add_u64 v[4:5], v[4:5], 0, s[84:85]
	global_store_dword v[4:5], v2, off

.LBB0_375:
	v_ashrrev_i32_e32 v135, 31, v134
	v_lshl_add_u64 v[138:139], v[134:135], 2, s[86:87]
	global_load_dword v0, v[138:139], off
	v_mov_b32_e32 v130, v126
	v_mov_b32_e32 v131, v118
	v_lshl_or_b32 v136, s19, 7, v149
	v_readlane_b32 s26, v252, 17
	v_ashrrev_i32_e32 v137, 31, v136
	v_readlane_b32 s27, v252, 18
	s_waitcnt vmcnt(0)
	v_pk_mul_f32 v[130:131], v[130:131], v[0:1] op_sel_hi:[1,0]
	s_nop 0
	v_mul_f32_e32 v130, v130, v131
	v_mul_f32_e32 v131, 0xbfb8aa3b, v131
	v_exp_f32_e32 v131, v131
	s_nop 0
	v_add_f32_e32 v131, 1.0, v131
	v_rcp_f32_e32 v131, v131
	s_nop 0
	v_mul_f32_e32 v132, v130, v131
	v_mov_b32_e32 v130, v122
	v_mov_b32_e32 v131, v114
	v_pk_mul_f32 v[130:131], v[130:131], v[0:1] op_sel_hi:[1,0]
	s_nop 0
	v_mul_f32_e32 v130, v130, v131
	v_mul_f32_e32 v131, 0xbfb8aa3b, v131
	v_exp_f32_e32 v131, v131
	s_nop 0
	v_add_f32_e32 v131, 1.0, v131
	v_rcp_f32_e32 v131, v131
	s_nop 0
	v_mul_f32_e32 v133, v130, v131
	v_mov_b32_e32 v130, v127
	v_mov_b32_e32 v131, v119
	v_pk_mul_f32 v[130:131], v[130:131], v[0:1] op_sel_hi:[1,0]
	s_nop 0
	v_mul_f32_e32 v130, v130, v131
	v_mul_f32_e32 v131, 0xbfb8aa3b, v131
	v_exp_f32_e32 v131, v131
	s_nop 0
	v_add_f32_e32 v131, 1.0, v131
	v_rcp_f32_e32 v131, v131
	s_nop 0
	v_mul_f32_e32 v140, v130, v131
	v_mov_b32_e32 v130, v123
	v_mov_b32_e32 v131, v115
	v_pk_mul_f32 v[130:131], v[130:131], v[0:1] op_sel_hi:[1,0]
	s_nop 0
	v_mul_f32_e32 v130, v130, v131
	v_mul_f32_e32 v131, 0xbfb8aa3b, v131
	v_exp_f32_e32 v131, v131
	s_nop 0
	v_add_f32_e32 v131, 1.0, v131
	v_rcp_f32_e32 v131, v131
	s_nop 0
	v_mul_f32_e32 v141, v130, v131
	v_mov_b32_e32 v130, v128
	v_mov_b32_e32 v131, v120
	v_pk_mul_f32 v[130:131], v[130:131], v[0:1] op_sel_hi:[1,0]
	s_nop 0
	v_mul_f32_e32 v130, v130, v131
	v_mul_f32_e32 v131, 0xbfb8aa3b, v131
	v_exp_f32_e32 v131, v131
	s_nop 0
	v_add_f32_e32 v131, 1.0, v131
	v_rcp_f32_e32 v131, v131
	s_nop 0
	v_mul_f32_e32 v142, v130, v131
	v_mov_b32_e32 v130, v124
	v_mov_b32_e32 v131, v116
	v_pk_mul_f32 v[130:131], v[130:131], v[0:1] op_sel_hi:[1,0]
	s_nop 0
	v_mul_f32_e32 v130, v130, v131
	v_mul_f32_e32 v131, 0xbfb8aa3b, v131
	v_exp_f32_e32 v131, v131
	s_nop 0
	v_add_f32_e32 v131, 1.0, v131
	v_rcp_f32_e32 v131, v131
	s_nop 0
	v_mul_f32_e32 v143, v130, v131
	v_mov_b32_e32 v130, v129
	v_mov_b32_e32 v131, v121
	v_pk_mul_f32 v[130:131], v[130:131], v[0:1] op_sel_hi:[1,0]
	s_nop 0
	v_mul_f32_e32 v130, v130, v131
	v_mul_f32_e32 v131, 0xbfb8aa3b, v131
	v_exp_f32_e32 v131, v131
	s_nop 0
	v_add_f32_e32 v131, 1.0, v131
	v_rcp_f32_e32 v131, v131
	s_nop 0
	v_mul_f32_e32 v152, v130, v131
	v_mov_b32_e32 v130, v125
	v_mov_b32_e32 v131, v117
	v_pk_mul_f32 v[130:131], v[130:131], v[0:1] op_sel_hi:[1,0]
	s_nop 0
	v_mul_f32_e32 v0, v130, v131
	v_mul_f32_e32 v130, 0xbfb8aa3b, v131
	v_exp_f32_e32 v130, v130
	s_nop 0
	v_add_f32_e32 v130, 1.0, v130
	v_rcp_f32_e32 v130, v130
	s_nop 0
	v_mul_f32_e32 v0, v0, v130
	v_cvt_pk_bf16_f32 v130, v132, v140
	v_cvt_pk_bf16_f32 v131, v142, v152
	v_cvt_pk_bf16_f32 v132, v133, v141
	v_lshlrev_b64 v[140:141], 12, v[134:135]
	v_cvt_pk_bf16_f32 v133, v143, v0
	v_lshl_add_u64 v[142:143], s[26:27], 0, v[140:141]
	v_lshlrev_b64 v[140:141], 1, v[136:137]
	v_lshl_add_u64 v[136:137], v[142:143], 0, v[140:141]
	global_store_dwordx4 v[136:137], v[130:133], off sc1
	global_load_dword v0, v[138:139], off offset:64
	v_or_b32_e32 v142, 16, v134
	v_mov_b32_e32 v130, v110
	v_mov_b32_e32 v131, v102
	v_ashrrev_i32_e32 v143, 31, v142
	v_lshlrev_b64 v[142:143], 12, v[142:143]
	v_lshl_add_u64 v[142:143], s[26:27], 0, v[142:143]
	v_lshl_add_u64 v[142:143], v[142:143], 0, v[140:141]
	s_waitcnt vmcnt(0)
	v_pk_mul_f32 v[130:131], v[130:131], v[0:1] op_sel_hi:[1,0]
	s_nop 0
	v_mul_f32_e32 v130, v130, v131
	v_mul_f32_e32 v131, 0xbfb8aa3b, v131
	v_exp_f32_e32 v131, v131
	s_nop 0
	v_add_f32_e32 v131, 1.0, v131
	v_rcp_f32_e32 v131, v131
	s_nop 0
	v_mul_f32_e32 v132, v130, v131
	v_mov_b32_e32 v130, v106
	v_mov_b32_e32 v131, v98
	v_pk_mul_f32 v[130:131], v[130:131], v[0:1] op_sel_hi:[1,0]
	s_nop 0
	v_mul_f32_e32 v130, v130, v131
	v_mul_f32_e32 v131, 0xbfb8aa3b, v131
	v_exp_f32_e32 v131, v131
	s_nop 0
	v_add_f32_e32 v131, 1.0, v131
	v_rcp_f32_e32 v131, v131
	s_nop 0
	v_mul_f32_e32 v133, v130, v131
	v_mov_b32_e32 v130, v111
	v_mov_b32_e32 v131, v103
	v_pk_mul_f32 v[130:131], v[130:131], v[0:1] op_sel_hi:[1,0]
	s_nop 0
	v_mul_f32_e32 v130, v130, v131
	v_mul_f32_e32 v131, 0xbfb8aa3b, v131
	v_exp_f32_e32 v131, v131
	s_nop 0
	v_add_f32_e32 v131, 1.0, v131
	v_rcp_f32_e32 v131, v131
	s_nop 0
	v_mul_f32_e32 v135, v130, v131
	v_mov_b32_e32 v130, v107
	v_mov_b32_e32 v131, v99
	v_pk_mul_f32 v[130:131], v[130:131], v[0:1] op_sel_hi:[1,0]
	s_nop 0
	v_mul_f32_e32 v130, v130, v131
	v_mul_f32_e32 v131, 0xbfb8aa3b, v131
	v_exp_f32_e32 v131, v131
	s_nop 0
	v_add_f32_e32 v131, 1.0, v131
	v_rcp_f32_e32 v131, v131
	s_nop 0
	v_mul_f32_e32 v152, v130, v131
	v_mov_b32_e32 v130, v112
	v_mov_b32_e32 v131, v104
	v_pk_mul_f32 v[130:131], v[130:131], v[0:1] op_sel_hi:[1,0]
	s_nop 0
	v_mul_f32_e32 v130, v130, v131
	v_mul_f32_e32 v131, 0xbfb8aa3b, v131
	v_exp_f32_e32 v131, v131
	s_nop 0
	v_add_f32_e32 v131, 1.0, v131
	v_rcp_f32_e32 v131, v131
	s_nop 0
	v_mul_f32_e32 v153, v130, v131
	v_mov_b32_e32 v130, v108
	v_mov_b32_e32 v131, v100
	v_pk_mul_f32 v[130:131], v[130:131], v[0:1] op_sel_hi:[1,0]
	s_nop 0
	v_mul_f32_e32 v130, v130, v131
	v_mul_f32_e32 v131, 0xbfb8aa3b, v131
	v_exp_f32_e32 v131, v131
	s_nop 0
	v_add_f32_e32 v131, 1.0, v131
	v_rcp_f32_e32 v131, v131
	s_nop 0
	v_mul_f32_e32 v154, v130, v131
	v_mov_b32_e32 v130, v113
	v_mov_b32_e32 v131, v105
	v_pk_mul_f32 v[130:131], v[130:131], v[0:1] op_sel_hi:[1,0]
	s_nop 0
	v_mul_f32_e32 v130, v130, v131
	v_mul_f32_e32 v131, 0xbfb8aa3b, v131
	v_exp_f32_e32 v131, v131
	s_nop 0
	v_add_f32_e32 v131, 1.0, v131
	v_rcp_f32_e32 v131, v131
	s_nop 0
	v_mul_f32_e32 v155, v130, v131
	v_mov_b32_e32 v130, v109
	v_mov_b32_e32 v131, v101
	v_pk_mul_f32 v[130:131], v[130:131], v[0:1] op_sel_hi:[1,0]
	s_nop 0
	v_mul_f32_e32 v0, v130, v131
	v_mul_f32_e32 v130, 0xbfb8aa3b, v131
	v_exp_f32_e32 v130, v130
	s_nop 0
	v_add_f32_e32 v130, 1.0, v130
	v_rcp_f32_e32 v130, v130
	s_nop 0
	v_mul_f32_e32 v0, v0, v130
	v_cvt_pk_bf16_f32 v130, v132, v135
	v_cvt_pk_bf16_f32 v131, v153, v155
	v_cvt_pk_bf16_f32 v132, v133, v152
	v_cvt_pk_bf16_f32 v133, v154, v0
	global_store_dwordx4 v[142:143], v[130:133], off sc1
	global_load_dword v0, v[138:139], off offset:128
	v_or_b32_e32 v142, 32, v134
	v_mov_b32_e32 v130, v94
	v_mov_b32_e32 v131, v86
	v_ashrrev_i32_e32 v143, 31, v142
	v_lshlrev_b64 v[142:143], 12, v[142:143]
	v_lshl_add_u64 v[142:143], s[26:27], 0, v[142:143]
	v_lshl_add_u64 v[142:143], v[142:143], 0, v[140:141]
	s_waitcnt vmcnt(0)
	v_pk_mul_f32 v[130:131], v[130:131], v[0:1] op_sel_hi:[1,0]
	s_nop 0
	v_mul_f32_e32 v130, v130, v131
	v_mul_f32_e32 v131, 0xbfb8aa3b, v131
	v_exp_f32_e32 v131, v131
	s_nop 0
	v_add_f32_e32 v131, 1.0, v131
	v_rcp_f32_e32 v131, v131
	s_nop 0
	v_mul_f32_e32 v132, v130, v131
	v_mov_b32_e32 v130, v90
	v_mov_b32_e32 v131, v82
	v_pk_mul_f32 v[130:131], v[130:131], v[0:1] op_sel_hi:[1,0]
	s_nop 0
	v_mul_f32_e32 v130, v130, v131
	v_mul_f32_e32 v131, 0xbfb8aa3b, v131
	v_exp_f32_e32 v131, v131
	s_nop 0
	v_add_f32_e32 v131, 1.0, v131
	v_rcp_f32_e32 v131, v131
	s_nop 0
	v_mul_f32_e32 v133, v130, v131
	v_mov_b32_e32 v130, v95
	v_mov_b32_e32 v131, v87
	v_pk_mul_f32 v[130:131], v[130:131], v[0:1] op_sel_hi:[1,0]
	s_nop 0
	v_mul_f32_e32 v130, v130, v131
	v_mul_f32_e32 v131, 0xbfb8aa3b, v131
	v_exp_f32_e32 v131, v131
	s_nop 0
	v_add_f32_e32 v131, 1.0, v131
	v_rcp_f32_e32 v131, v131
	s_nop 0
	v_mul_f32_e32 v135, v130, v131
	v_mov_b32_e32 v130, v91
	v_mov_b32_e32 v131, v83
	v_pk_mul_f32 v[130:131], v[130:131], v[0:1] op_sel_hi:[1,0]
	s_nop 0
	v_mul_f32_e32 v130, v130, v131
	v_mul_f32_e32 v131, 0xbfb8aa3b, v131
	v_exp_f32_e32 v131, v131
	s_nop 0
	v_add_f32_e32 v131, 1.0, v131
	v_rcp_f32_e32 v131, v131
	s_nop 0
	v_mul_f32_e32 v152, v130, v131
	v_mov_b32_e32 v130, v96
	v_mov_b32_e32 v131, v88
	v_pk_mul_f32 v[130:131], v[130:131], v[0:1] op_sel_hi:[1,0]
	s_nop 0
	v_mul_f32_e32 v130, v130, v131
	v_mul_f32_e32 v131, 0xbfb8aa3b, v131
	v_exp_f32_e32 v131, v131
	s_nop 0
	v_add_f32_e32 v131, 1.0, v131
	v_rcp_f32_e32 v131, v131
	s_nop 0
	v_mul_f32_e32 v153, v130, v131
	v_mov_b32_e32 v130, v92
	v_mov_b32_e32 v131, v84
	v_pk_mul_f32 v[130:131], v[130:131], v[0:1] op_sel_hi:[1,0]
	s_nop 0
	v_mul_f32_e32 v130, v130, v131
	v_mul_f32_e32 v131, 0xbfb8aa3b, v131
	v_exp_f32_e32 v131, v131
	s_nop 0
	v_add_f32_e32 v131, 1.0, v131
	v_rcp_f32_e32 v131, v131
	s_nop 0
	v_mul_f32_e32 v154, v130, v131
	v_mov_b32_e32 v130, v97
	v_mov_b32_e32 v131, v89
	v_pk_mul_f32 v[130:131], v[130:131], v[0:1] op_sel_hi:[1,0]
	s_nop 0
	v_mul_f32_e32 v130, v130, v131
	v_mul_f32_e32 v131, 0xbfb8aa3b, v131
	v_exp_f32_e32 v131, v131
	s_nop 0
	v_add_f32_e32 v131, 1.0, v131
	v_rcp_f32_e32 v131, v131
	s_nop 0
	v_mul_f32_e32 v155, v130, v131
	v_mov_b32_e32 v130, v93
	v_mov_b32_e32 v131, v85
	v_pk_mul_f32 v[130:131], v[130:131], v[0:1] op_sel_hi:[1,0]
	s_nop 0
	v_mul_f32_e32 v0, v130, v131
	v_mul_f32_e32 v130, 0xbfb8aa3b, v131
	v_exp_f32_e32 v130, v130
	s_nop 0
	v_add_f32_e32 v130, 1.0, v130
	v_rcp_f32_e32 v130, v130
	s_nop 0
	v_mul_f32_e32 v0, v0, v130
	v_cvt_pk_bf16_f32 v130, v132, v135
	v_cvt_pk_bf16_f32 v131, v153, v155
	v_cvt_pk_bf16_f32 v132, v133, v152
	v_cvt_pk_bf16_f32 v133, v154, v0
	global_store_dwordx4 v[142:143], v[130:133], off sc1
	global_load_dword v0, v[138:139], off offset:192
	v_or_b32_e32 v142, 48, v134
	v_mov_b32_e32 v130, v78
	v_mov_b32_e32 v131, v70
	v_ashrrev_i32_e32 v143, 31, v142
	v_lshlrev_b64 v[142:143], 12, v[142:143]
	v_lshl_add_u64 v[142:143], s[26:27], 0, v[142:143]
	v_lshl_add_u64 v[140:141], v[142:143], 0, v[140:141]
	s_mov_b32 s26, 0x80000
	s_waitcnt vmcnt(0)
	v_pk_mul_f32 v[130:131], v[130:131], v[0:1] op_sel_hi:[1,0]
	s_nop 0
	v_mul_f32_e32 v130, v130, v131
	v_mul_f32_e32 v131, 0xbfb8aa3b, v131
	v_exp_f32_e32 v131, v131
	s_nop 0
	v_add_f32_e32 v131, 1.0, v131
	v_rcp_f32_e32 v131, v131
	s_nop 0
	v_mul_f32_e32 v132, v130, v131
	v_mov_b32_e32 v130, v74
	v_mov_b32_e32 v131, v66
	v_pk_mul_f32 v[130:131], v[130:131], v[0:1] op_sel_hi:[1,0]
	s_nop 0
	v_mul_f32_e32 v130, v130, v131
	v_mul_f32_e32 v131, 0xbfb8aa3b, v131
	v_exp_f32_e32 v131, v131
	s_nop 0
	v_add_f32_e32 v131, 1.0, v131
	v_rcp_f32_e32 v131, v131
	s_nop 0
	v_mul_f32_e32 v133, v130, v131
	v_mov_b32_e32 v130, v79
	v_mov_b32_e32 v131, v71
	v_pk_mul_f32 v[130:131], v[130:131], v[0:1] op_sel_hi:[1,0]
	s_nop 0
	v_mul_f32_e32 v130, v130, v131
	v_mul_f32_e32 v131, 0xbfb8aa3b, v131
	v_exp_f32_e32 v131, v131
	s_nop 0
	v_add_f32_e32 v131, 1.0, v131
	v_rcp_f32_e32 v131, v131
	s_nop 0
	v_mul_f32_e32 v135, v130, v131
	v_mov_b32_e32 v130, v75
	v_mov_b32_e32 v131, v67
	v_pk_mul_f32 v[130:131], v[130:131], v[0:1] op_sel_hi:[1,0]
	s_nop 0
	v_mul_f32_e32 v130, v130, v131
	v_mul_f32_e32 v131, 0xbfb8aa3b, v131
	v_exp_f32_e32 v131, v131
	s_nop 0
	v_add_f32_e32 v131, 1.0, v131
	v_rcp_f32_e32 v131, v131
	s_nop 0
	v_mul_f32_e32 v152, v130, v131
	v_mov_b32_e32 v130, v80
	v_mov_b32_e32 v131, v72
	v_pk_mul_f32 v[130:131], v[130:131], v[0:1] op_sel_hi:[1,0]
	s_nop 0
	v_mul_f32_e32 v130, v130, v131
	v_mul_f32_e32 v131, 0xbfb8aa3b, v131
	v_exp_f32_e32 v131, v131
	s_nop 0
	v_add_f32_e32 v131, 1.0, v131
	v_rcp_f32_e32 v131, v131
	s_nop 0
	v_mul_f32_e32 v153, v130, v131
	v_mov_b32_e32 v130, v76
	v_mov_b32_e32 v131, v68
	v_pk_mul_f32 v[130:131], v[130:131], v[0:1] op_sel_hi:[1,0]
	s_nop 0
	v_mul_f32_e32 v130, v130, v131
	v_mul_f32_e32 v131, 0xbfb8aa3b, v131
	v_exp_f32_e32 v131, v131
	s_nop 0
	v_add_f32_e32 v131, 1.0, v131
	v_rcp_f32_e32 v131, v131
	s_nop 0
	v_mul_f32_e32 v154, v130, v131
	v_mov_b32_e32 v130, v81
	v_mov_b32_e32 v131, v73
	v_pk_mul_f32 v[130:131], v[130:131], v[0:1] op_sel_hi:[1,0]
	s_nop 0
	v_mul_f32_e32 v130, v130, v131
	v_mul_f32_e32 v131, 0xbfb8aa3b, v131
	v_exp_f32_e32 v131, v131
	s_nop 0
	v_add_f32_e32 v131, 1.0, v131
	v_rcp_f32_e32 v131, v131
	s_nop 0
	v_mul_f32_e32 v155, v130, v131
	v_mov_b32_e32 v130, v77
	v_mov_b32_e32 v131, v69
	v_pk_mul_f32 v[130:131], v[130:131], v[0:1] op_sel_hi:[1,0]
	s_nop 0
	v_mul_f32_e32 v0, v130, v131
	v_mul_f32_e32 v130, 0xbfb8aa3b, v131
	v_exp_f32_e32 v130, v130
	s_nop 0
	v_add_f32_e32 v130, 1.0, v130
	v_rcp_f32_e32 v130, v130
	s_nop 0
	v_mul_f32_e32 v0, v0, v130
	v_cvt_pk_bf16_f32 v130, v132, v135
	v_cvt_pk_bf16_f32 v131, v153, v155
	v_cvt_pk_bf16_f32 v132, v133, v152
	v_cvt_pk_bf16_f32 v133, v154, v0
	global_store_dwordx4 v[140:141], v[130:133], off sc1
	global_load_dword v0, v[138:139], off offset:512
	s_nop 0
	v_mov_b32_e32 v130, v62
	v_mov_b32_e32 v131, v54
	s_waitcnt vmcnt(0)
	v_pk_mul_f32 v[130:131], v[130:131], v[0:1] op_sel_hi:[1,0]
	s_nop 0
	v_mul_f32_e32 v130, v130, v131
	v_mul_f32_e32 v131, 0xbfb8aa3b, v131
	v_exp_f32_e32 v131, v131
	s_nop 0
	v_add_f32_e32 v131, 1.0, v131
	v_rcp_f32_e32 v131, v131
	s_nop 0
	v_mul_f32_e32 v132, v130, v131
	v_mov_b32_e32 v130, v58
	v_mov_b32_e32 v131, v50
	v_pk_mul_f32 v[130:131], v[130:131], v[0:1] op_sel_hi:[1,0]
	s_nop 0
	v_mul_f32_e32 v130, v130, v131
	v_mul_f32_e32 v131, 0xbfb8aa3b, v131
	v_exp_f32_e32 v131, v131
	s_nop 0
	v_add_f32_e32 v131, 1.0, v131
	v_rcp_f32_e32 v131, v131
	s_nop 0
	v_mul_f32_e32 v133, v130, v131
	v_mov_b32_e32 v130, v63
	v_mov_b32_e32 v131, v55
	v_pk_mul_f32 v[130:131], v[130:131], v[0:1] op_sel_hi:[1,0]
	s_nop 0
	v_mul_f32_e32 v130, v130, v131
	v_mul_f32_e32 v131, 0xbfb8aa3b, v131
	v_exp_f32_e32 v131, v131
	s_nop 0
	v_add_f32_e32 v131, 1.0, v131
	v_rcp_f32_e32 v131, v131
	s_nop 0
	v_mul_f32_e32 v135, v130, v131
	v_mov_b32_e32 v130, v59
	v_mov_b32_e32 v131, v51
	v_pk_mul_f32 v[130:131], v[130:131], v[0:1] op_sel_hi:[1,0]
	s_nop 0
	v_mul_f32_e32 v130, v130, v131
	v_mul_f32_e32 v131, 0xbfb8aa3b, v131
	v_exp_f32_e32 v131, v131
	s_nop 0
	v_add_f32_e32 v131, 1.0, v131
	v_rcp_f32_e32 v131, v131
	s_nop 0
	v_mul_f32_e32 v140, v130, v131
	v_mov_b32_e32 v130, v64
	v_mov_b32_e32 v131, v56
	v_pk_mul_f32 v[130:131], v[130:131], v[0:1] op_sel_hi:[1,0]
	s_nop 0
	v_mul_f32_e32 v130, v130, v131
	v_mul_f32_e32 v131, 0xbfb8aa3b, v131
	v_exp_f32_e32 v131, v131
	s_nop 0
	v_add_f32_e32 v131, 1.0, v131
	v_rcp_f32_e32 v131, v131
	s_nop 0
	v_mul_f32_e32 v141, v130, v131
	v_mov_b32_e32 v130, v60
	v_mov_b32_e32 v131, v52
	v_pk_mul_f32 v[130:131], v[130:131], v[0:1] op_sel_hi:[1,0]
	s_nop 0
	v_mul_f32_e32 v130, v130, v131
	v_mul_f32_e32 v131, 0xbfb8aa3b, v131
	v_exp_f32_e32 v131, v131
	s_nop 0
	v_add_f32_e32 v131, 1.0, v131
	v_rcp_f32_e32 v131, v131
	s_nop 0
	v_mul_f32_e32 v142, v130, v131
	v_mov_b32_e32 v130, v65
	v_mov_b32_e32 v131, v57
	v_pk_mul_f32 v[130:131], v[130:131], v[0:1] op_sel_hi:[1,0]
	s_nop 0
	v_mul_f32_e32 v130, v130, v131
	v_mul_f32_e32 v131, 0xbfb8aa3b, v131
	v_exp_f32_e32 v131, v131
	s_nop 0
	v_add_f32_e32 v131, 1.0, v131
	v_rcp_f32_e32 v131, v131
	s_nop 0
	v_mul_f32_e32 v143, v130, v131
	v_mov_b32_e32 v130, v61
	v_mov_b32_e32 v131, v53
	v_pk_mul_f32 v[130:131], v[130:131], v[0:1] op_sel_hi:[1,0]
	s_nop 0
	v_mul_f32_e32 v0, v130, v131
	v_mul_f32_e32 v130, 0xbfb8aa3b, v131
	v_exp_f32_e32 v130, v130
	s_nop 0
	v_add_f32_e32 v130, 1.0, v130
	v_rcp_f32_e32 v130, v130
	s_nop 0
	v_mul_f32_e32 v0, v0, v130
	v_cvt_pk_bf16_f32 v130, v132, v135
	v_cvt_pk_bf16_f32 v131, v141, v143
	v_cvt_pk_bf16_f32 v132, v133, v140
	v_add_co_u32_e32 v140, vcc, s26, v136
	v_cvt_pk_bf16_f32 v133, v142, v0
	s_mov_b32 s26, 0x90000
	s_nop 0
	v_addc_co_u32_e32 v141, vcc, 0, v137, vcc
	global_store_dwordx4 v[140:141], v[130:133], off sc1
	global_load_dword v0, v[138:139], off offset:576
	s_nop 0
	v_mov_b32_e32 v130, v46
	v_mov_b32_e32 v131, v38
	s_waitcnt vmcnt(0)
	v_pk_mul_f32 v[130:131], v[130:131], v[0:1] op_sel_hi:[1,0]
	s_nop 0
	v_mul_f32_e32 v130, v130, v131
	v_mul_f32_e32 v131, 0xbfb8aa3b, v131
	v_exp_f32_e32 v131, v131
	s_nop 0
	v_add_f32_e32 v131, 1.0, v131
	v_rcp_f32_e32 v131, v131
	s_nop 0
	v_mul_f32_e32 v132, v130, v131
	v_mov_b32_e32 v130, v42
	v_mov_b32_e32 v131, v34
	v_pk_mul_f32 v[130:131], v[130:131], v[0:1] op_sel_hi:[1,0]
	s_nop 0
	v_mul_f32_e32 v130, v130, v131
	v_mul_f32_e32 v131, 0xbfb8aa3b, v131
	v_exp_f32_e32 v131, v131
	s_nop 0
	v_add_f32_e32 v131, 1.0, v131
	v_rcp_f32_e32 v131, v131
	s_nop 0
	v_mul_f32_e32 v133, v130, v131
	v_mov_b32_e32 v130, v47
	v_mov_b32_e32 v131, v39
	v_pk_mul_f32 v[130:131], v[130:131], v[0:1] op_sel_hi:[1,0]
	s_nop 0
	v_mul_f32_e32 v130, v130, v131
	v_mul_f32_e32 v131, 0xbfb8aa3b, v131
	v_exp_f32_e32 v131, v131
	s_nop 0
	v_add_f32_e32 v131, 1.0, v131
	v_rcp_f32_e32 v131, v131
	s_nop 0
	v_mul_f32_e32 v135, v130, v131
	v_mov_b32_e32 v130, v43
	v_mov_b32_e32 v131, v35
	v_pk_mul_f32 v[130:131], v[130:131], v[0:1] op_sel_hi:[1,0]
	s_nop 0
	v_mul_f32_e32 v130, v130, v131
	v_mul_f32_e32 v131, 0xbfb8aa3b, v131
	v_exp_f32_e32 v131, v131
	s_nop 0
	v_add_f32_e32 v131, 1.0, v131
	v_rcp_f32_e32 v131, v131
	s_nop 0
	v_mul_f32_e32 v140, v130, v131
	v_mov_b32_e32 v130, v48
	v_mov_b32_e32 v131, v40
	v_pk_mul_f32 v[130:131], v[130:131], v[0:1] op_sel_hi:[1,0]
	s_nop 0
	v_mul_f32_e32 v130, v130, v131
	v_mul_f32_e32 v131, 0xbfb8aa3b, v131
	v_exp_f32_e32 v131, v131
	s_nop 0
	v_add_f32_e32 v131, 1.0, v131
	v_rcp_f32_e32 v131, v131
	s_nop 0
	v_mul_f32_e32 v141, v130, v131
	v_mov_b32_e32 v130, v44
	v_mov_b32_e32 v131, v36
	v_pk_mul_f32 v[130:131], v[130:131], v[0:1] op_sel_hi:[1,0]
	s_nop 0
	v_mul_f32_e32 v130, v130, v131
	v_mul_f32_e32 v131, 0xbfb8aa3b, v131
	v_exp_f32_e32 v131, v131
	s_nop 0
	v_add_f32_e32 v131, 1.0, v131
	v_rcp_f32_e32 v131, v131
	s_nop 0
	v_mul_f32_e32 v142, v130, v131
	v_mov_b32_e32 v130, v49
	v_mov_b32_e32 v131, v41
	v_pk_mul_f32 v[130:131], v[130:131], v[0:1] op_sel_hi:[1,0]
	s_nop 0
	v_mul_f32_e32 v130, v130, v131
	v_mul_f32_e32 v131, 0xbfb8aa3b, v131
	v_exp_f32_e32 v131, v131
	s_nop 0
	v_add_f32_e32 v131, 1.0, v131
	v_rcp_f32_e32 v131, v131
	s_nop 0
	v_mul_f32_e32 v143, v130, v131
	v_mov_b32_e32 v130, v45
	v_mov_b32_e32 v131, v37
	v_pk_mul_f32 v[130:131], v[130:131], v[0:1] op_sel_hi:[1,0]
	s_nop 0
	v_mul_f32_e32 v0, v130, v131
	v_mul_f32_e32 v130, 0xbfb8aa3b, v131
	v_exp_f32_e32 v130, v130
	s_nop 0
	v_add_f32_e32 v130, 1.0, v130
	v_rcp_f32_e32 v130, v130
	s_nop 0
	v_mul_f32_e32 v0, v0, v130
	v_cvt_pk_bf16_f32 v130, v132, v135
	v_cvt_pk_bf16_f32 v131, v141, v143
	v_cvt_pk_bf16_f32 v132, v133, v140
	v_add_co_u32_e32 v140, vcc, s26, v136
	v_cvt_pk_bf16_f32 v133, v142, v0
	s_mov_b32 s26, 0xa0000
	s_nop 0
	v_addc_co_u32_e32 v141, vcc, 0, v137, vcc
	global_store_dwordx4 v[140:141], v[130:133], off sc1
	global_load_dword v0, v[138:139], off offset:640
	s_nop 0
	v_mov_b32_e32 v130, v30
	v_mov_b32_e32 v131, v22
	s_waitcnt vmcnt(0)
	v_pk_mul_f32 v[130:131], v[130:131], v[0:1] op_sel_hi:[1,0]
	s_nop 0
	v_mul_f32_e32 v130, v130, v131
	v_mul_f32_e32 v131, 0xbfb8aa3b, v131
	v_exp_f32_e32 v131, v131
	s_nop 0
	v_add_f32_e32 v131, 1.0, v131
	v_rcp_f32_e32 v131, v131
	s_nop 0
	v_mul_f32_e32 v132, v130, v131
	v_mov_b32_e32 v130, v26
	v_mov_b32_e32 v131, v18
	v_pk_mul_f32 v[130:131], v[130:131], v[0:1] op_sel_hi:[1,0]
	s_nop 0
	v_mul_f32_e32 v130, v130, v131
	v_mul_f32_e32 v131, 0xbfb8aa3b, v131
	v_exp_f32_e32 v131, v131
	s_nop 0
	v_add_f32_e32 v131, 1.0, v131
	v_rcp_f32_e32 v131, v131
	s_nop 0
	v_mul_f32_e32 v133, v130, v131
	v_mov_b32_e32 v130, v31
	v_mov_b32_e32 v131, v23
	v_pk_mul_f32 v[130:131], v[130:131], v[0:1] op_sel_hi:[1,0]
	s_nop 0
	v_mul_f32_e32 v130, v130, v131
	v_mul_f32_e32 v131, 0xbfb8aa3b, v131
	v_exp_f32_e32 v131, v131
	s_nop 0
	v_add_f32_e32 v131, 1.0, v131
	v_rcp_f32_e32 v131, v131
	s_nop 0
	v_mul_f32_e32 v135, v130, v131
	v_mov_b32_e32 v130, v27
	v_mov_b32_e32 v131, v19
	v_pk_mul_f32 v[130:131], v[130:131], v[0:1] op_sel_hi:[1,0]
	s_nop 0
	v_mul_f32_e32 v130, v130, v131
	v_mul_f32_e32 v131, 0xbfb8aa3b, v131
	v_exp_f32_e32 v131, v131
	s_nop 0
	v_add_f32_e32 v131, 1.0, v131
	v_rcp_f32_e32 v131, v131
	s_nop 0
	v_mul_f32_e32 v140, v130, v131
	v_mov_b32_e32 v130, v32
	v_mov_b32_e32 v131, v24
	v_pk_mul_f32 v[130:131], v[130:131], v[0:1] op_sel_hi:[1,0]
	s_nop 0
	v_mul_f32_e32 v130, v130, v131
	v_mul_f32_e32 v131, 0xbfb8aa3b, v131
	v_exp_f32_e32 v131, v131
	s_nop 0
	v_add_f32_e32 v131, 1.0, v131
	v_rcp_f32_e32 v131, v131
	s_nop 0
	v_mul_f32_e32 v141, v130, v131
	v_mov_b32_e32 v130, v28
	v_mov_b32_e32 v131, v20
	v_pk_mul_f32 v[130:131], v[130:131], v[0:1] op_sel_hi:[1,0]
	s_nop 0
	v_mul_f32_e32 v130, v130, v131
	v_mul_f32_e32 v131, 0xbfb8aa3b, v131
	v_exp_f32_e32 v131, v131
	s_nop 0
	v_add_f32_e32 v131, 1.0, v131
	v_rcp_f32_e32 v131, v131
	s_nop 0
	v_mul_f32_e32 v142, v130, v131
	v_mov_b32_e32 v130, v33
	v_mov_b32_e32 v131, v25
	v_pk_mul_f32 v[130:131], v[130:131], v[0:1] op_sel_hi:[1,0]
	s_nop 0
	v_mul_f32_e32 v130, v130, v131
	v_mul_f32_e32 v131, 0xbfb8aa3b, v131
	v_exp_f32_e32 v131, v131
	s_nop 0
	v_add_f32_e32 v131, 1.0, v131
	v_rcp_f32_e32 v131, v131
	s_nop 0
	v_mul_f32_e32 v143, v130, v131
	v_mov_b32_e32 v130, v29
	v_mov_b32_e32 v131, v21
	v_pk_mul_f32 v[130:131], v[130:131], v[0:1] op_sel_hi:[1,0]
	s_nop 0
	v_mul_f32_e32 v0, v130, v131
	v_mul_f32_e32 v130, 0xbfb8aa3b, v131
	v_exp_f32_e32 v130, v130
	s_nop 0
	v_add_f32_e32 v130, 1.0, v130
	v_rcp_f32_e32 v130, v130
	s_nop 0
	v_mul_f32_e32 v0, v0, v130
	v_cvt_pk_bf16_f32 v130, v132, v135
	v_cvt_pk_bf16_f32 v131, v141, v143
	v_cvt_pk_bf16_f32 v132, v133, v140
	v_add_co_u32_e32 v140, vcc, s26, v136
	v_cvt_pk_bf16_f32 v133, v142, v0
	s_nop 1
	v_addc_co_u32_e32 v141, vcc, 0, v137, vcc
	global_store_dwordx4 v[140:141], v[130:133], off sc1
	global_load_dword v0, v[138:139], off offset:704
	v_add_co_u32_e32 v136, vcc, 0xb0000, v136
	v_mov_b32_e32 v130, v14
	v_mov_b32_e32 v131, v6
	v_addc_co_u32_e32 v137, vcc, 0, v137, vcc
	s_waitcnt vmcnt(0)
	v_pk_mul_f32 v[130:131], v[130:131], v[0:1] op_sel_hi:[1,0]
	s_nop 0
	v_mul_f32_e32 v130, v130, v131
	v_mul_f32_e32 v131, 0xbfb8aa3b, v131
	v_exp_f32_e32 v131, v131
	s_nop 0
	v_add_f32_e32 v131, 1.0, v131
	v_rcp_f32_e32 v131, v131
	s_nop 0
	v_mul_f32_e32 v132, v130, v131
	v_mov_b32_e32 v130, v10
	v_mov_b32_e32 v131, v2
	v_pk_mul_f32 v[130:131], v[130:131], v[0:1] op_sel_hi:[1,0]
	s_nop 0
	v_mul_f32_e32 v130, v130, v131
	v_mul_f32_e32 v131, 0xbfb8aa3b, v131
	v_exp_f32_e32 v131, v131
	s_nop 0
	v_add_f32_e32 v131, 1.0, v131
	v_rcp_f32_e32 v131, v131
	s_nop 0
	v_mul_f32_e32 v133, v130, v131
	v_mov_b32_e32 v130, v15
	v_mov_b32_e32 v131, v7
	v_pk_mul_f32 v[130:131], v[130:131], v[0:1] op_sel_hi:[1,0]
	s_nop 0
	v_mul_f32_e32 v130, v130, v131
	v_mul_f32_e32 v131, 0xbfb8aa3b, v131
	v_exp_f32_e32 v131, v131
	s_nop 0
	v_add_f32_e32 v131, 1.0, v131
	v_rcp_f32_e32 v131, v131
	s_nop 0
	v_mul_f32_e32 v135, v130, v131
	v_mov_b32_e32 v130, v11
	v_mov_b32_e32 v131, v3
	v_pk_mul_f32 v[130:131], v[130:131], v[0:1] op_sel_hi:[1,0]
	s_nop 0
	v_mul_f32_e32 v130, v130, v131
	v_mul_f32_e32 v131, 0xbfb8aa3b, v131
	v_exp_f32_e32 v131, v131
	s_nop 0
	v_add_f32_e32 v131, 1.0, v131
	v_rcp_f32_e32 v131, v131
	s_nop 0
	v_mul_f32_e32 v138, v130, v131
	v_mov_b32_e32 v130, v16
	v_mov_b32_e32 v131, v8
	v_pk_mul_f32 v[130:131], v[130:131], v[0:1] op_sel_hi:[1,0]
	s_nop 0
	v_mul_f32_e32 v130, v130, v131
	v_mul_f32_e32 v131, 0xbfb8aa3b, v131
	v_exp_f32_e32 v131, v131
	s_nop 0
	v_add_f32_e32 v131, 1.0, v131
	v_rcp_f32_e32 v131, v131
	s_nop 0
	v_mul_f32_e32 v139, v130, v131
	v_mov_b32_e32 v130, v12
	v_mov_b32_e32 v131, v4
	v_pk_mul_f32 v[130:131], v[130:131], v[0:1] op_sel_hi:[1,0]
	s_nop 0
	v_mul_f32_e32 v130, v130, v131
	v_mul_f32_e32 v131, 0xbfb8aa3b, v131
	v_exp_f32_e32 v131, v131
	s_nop 0
	v_add_f32_e32 v131, 1.0, v131
	v_rcp_f32_e32 v131, v131
	s_nop 0
	v_mul_f32_e32 v140, v130, v131
	v_mov_b32_e32 v130, v17
	v_mov_b32_e32 v131, v9
	v_pk_mul_f32 v[130:131], v[130:131], v[0:1] op_sel_hi:[1,0]
	s_nop 0
	v_mul_f32_e32 v130, v130, v131
	v_mul_f32_e32 v131, 0xbfb8aa3b, v131
	v_exp_f32_e32 v131, v131
	s_nop 0
	v_add_f32_e32 v131, 1.0, v131
	v_rcp_f32_e32 v131, v131
	s_nop 0
	v_mul_f32_e32 v141, v130, v131
	v_mov_b32_e32 v130, v13
	v_mov_b32_e32 v131, v5
	v_pk_mul_f32 v[130:131], v[130:131], v[0:1] op_sel_hi:[1,0]
	s_nop 0
	v_mul_f32_e32 v0, v130, v131
	v_mul_f32_e32 v130, 0xbfb8aa3b, v131
	v_exp_f32_e32 v130, v130
	s_nop 0
	v_add_f32_e32 v130, 1.0, v130
	v_rcp_f32_e32 v130, v130
	s_nop 0
	v_mul_f32_e32 v0, v0, v130
	v_cvt_pk_bf16_f32 v130, v132, v135
	v_cvt_pk_bf16_f32 v131, v139, v141
	v_cvt_pk_bf16_f32 v132, v133, v138
	v_cvt_pk_bf16_f32 v133, v140, v0
	global_store_dwordx4 v[136:137], v[130:133], off sc1

.LBB0_383:
	s_xor_b64 s[26:27], s[96:97], -1
	s_lshl_b64 s[44:45], s[46:47], 1
	v_readlane_b32 s46, v252, 17
	v_readlane_b32 s47, v252, 18
	s_add_u32 s44, s46, s44
	v_add_u32_e32 v122, s48, v149
	s_addc_u32 s45, s47, s45
	v_ashrrev_i32_e32 v123, 31, v122
	v_cvt_pk_bf16_f32 v126, v126, v127
	v_cvt_pk_bf16_f32 v127, v128, v129
	v_cvt_pk_bf16_f32 v128, v136, v137
	v_cvt_pk_bf16_f32 v129, v124, v125
	v_mov_b32_e32 v124, v132
	v_mov_b32_e32 v125, v132
	v_mov_b32_e32 v133, v132
	v_lshl_add_u64 v[122:123], v[122:123], 1, s[44:45]
	v_lshlrev_b64 v[138:139], 12, v[134:135]
	v_pk_mul_f32 v[120:121], v[120:121], v[124:125]
	v_pk_mul_f32 v[116:117], v[116:117], v[124:125]
	v_cndmask_b32_e64 v124, 0, 1, s[26:27]
	v_lshl_add_u64 v[138:139], v[122:123], 0, v[138:139]
	v_pk_mul_f32 v[118:119], v[118:119], v[132:133]
	v_pk_mul_f32 v[114:115], v[114:115], v[132:133]
	v_cmp_ne_u32_e64 s[44:45], 1, v124
	s_andn2_b64 vcc, exec, s[26:27]
	s_mov_b64 s[26:27], -1
	global_store_dwordx4 v[138:139], v[126:129], off sc1
	s_cbranch_vccnz .LBB0_385
	s_mov_b64 s[26:27], 0

.LBB0_387:
	v_cvt_pk_bf16_f32 v118, v118, v119
	v_cvt_pk_bf16_f32 v119, v120, v121
	v_cvt_pk_bf16_f32 v120, v114, v115
	v_cndmask_b32_e64 v114, 0, 1, s[96:97]
	v_cmp_ne_u32_e64 s[46:47], 1, v114
	s_andn2_b64 vcc, exec, s[96:97]
	v_cvt_pk_bf16_f32 v121, v116, v117
	global_store_dwordx4 v[138:139], v[118:121], off offset:256 sc1
	s_cbranch_vccnz .LBB0_391
	v_and_b32_e32 v115, 64, v222
	v_xor_b32_e32 v114, 16, v222
	v_add_u32_e32 v115, 64, v115
	v_cmp_lt_i32_e32 vcc, v114, v115
	v_xor_b32_e32 v116, 32, v222
	s_nop 0
	v_cndmask_b32_e32 v114, v222, v114, vcc
	v_lshlrev_b32_e32 v114, 2, v114
	ds_bpermute_b32 v114, v114, v140
	v_cmp_lt_i32_e32 vcc, v116, v115
	s_waitcnt lgkmcnt(0)
	v_add_f32_e32 v114, v140, v114
	v_cndmask_b32_e32 v115, v222, v116, vcc
	v_lshlrev_b32_e32 v115, 2, v115
	ds_bpermute_b32 v115, v115, v114
	s_and_saveexec_b64 s[26:27], s[40:41]
	s_cbranch_execz .LBB0_390
	s_sub_i32 s48, s19, s17
	v_readlane_b32 s68, v252, 15
	s_waitcnt lgkmcnt(0)
	v_add_f32_e32 v116, v114, v115
	s_lshl_b32 s48, s48, 2
	v_lshlrev_b64 v[114:115], 7, v[134:135]
	v_readlane_b32 s69, v252, 16
	s_ashr_i32 s49, s48, 31
	s_lshl_b32 s84, s3, 2
	v_lshl_add_u64 v[114:115], s[68:69], 0, v[114:115]
	v_lshl_add_u64 v[114:115], s[48:49], 2, v[114:115]
	v_lshl_add_u64 v[114:115], v[114:115], 0, s[84:85]
	global_store_dword v[114:115], v116, off

.LBB0_395:
	v_or_b32_e32 v106, 16, v134
	v_ashrrev_i32_e32 v107, 31, v106
	v_mov_b32_e32 v115, v114
	v_lshlrev_b64 v[108:109], 12, v[106:107]
	v_cvt_pk_bf16_f32 v116, v116, v117
	v_cvt_pk_bf16_f32 v117, v112, v113
	v_cvt_pk_bf16_f32 v118, v118, v119
	v_cvt_pk_bf16_f32 v119, v110, v111
	v_mov_b32_e32 v110, v114
	v_mov_b32_e32 v111, v114
	v_lshl_add_u64 v[108:109], v[122:123], 0, v[108:109]
	v_pk_mul_f32 v[104:105], v[104:105], v[110:111]
	v_pk_mul_f32 v[102:103], v[102:103], v[114:115]
	v_pk_mul_f32 v[100:101], v[100:101], v[110:111]
	v_pk_mul_f32 v[98:99], v[98:99], v[114:115]
	s_and_b64 vcc, exec, s[44:45]
	s_mov_b64 s[26:27], -1
	global_store_dwordx4 v[108:109], v[116:119], off sc1
	s_cbranch_vccnz .LBB0_397
	s_mov_b64 s[26:27], 0

.LBB0_399:
	s_and_b64 vcc, exec, s[46:47]
	v_cvt_pk_bf16_f32 v102, v102, v103
	v_cvt_pk_bf16_f32 v103, v104, v105
	v_cvt_pk_bf16_f32 v104, v98, v99
	v_cvt_pk_bf16_f32 v105, v100, v101
	global_store_dwordx4 v[108:109], v[102:105], off offset:256 sc1
	s_cbranch_vccnz .LBB0_403
	v_and_b32_e32 v99, 64, v222
	v_xor_b32_e32 v98, 16, v222
	v_add_u32_e32 v99, 64, v99
	v_cmp_lt_i32_e32 vcc, v98, v99
	v_xor_b32_e32 v100, 32, v222
	s_nop 0
	v_cndmask_b32_e32 v98, v222, v98, vcc
	v_lshlrev_b32_e32 v98, 2, v98
	ds_bpermute_b32 v98, v98, v120
	v_cmp_lt_i32_e32 vcc, v100, v99
	s_waitcnt lgkmcnt(0)
	v_add_f32_e32 v98, v120, v98
	v_cndmask_b32_e32 v99, v222, v100, vcc
	v_lshlrev_b32_e32 v99, 2, v99
	ds_bpermute_b32 v99, v99, v98
	s_and_saveexec_b64 s[26:27], s[40:41]
	s_cbranch_execz .LBB0_402
	s_sub_i32 s48, s19, s17
	v_readlane_b32 s68, v252, 15
	s_waitcnt lgkmcnt(0)
	v_add_f32_e32 v100, v98, v99
	s_lshl_b32 s48, s48, 2
	v_lshlrev_b64 v[98:99], 7, v[106:107]
	v_readlane_b32 s69, v252, 16
	s_ashr_i32 s49, s48, 31
	s_lshl_b32 s84, s3, 2
	v_lshl_add_u64 v[98:99], s[68:69], 0, v[98:99]
	v_lshl_add_u64 v[98:99], s[48:49], 2, v[98:99]
	v_lshl_add_u64 v[98:99], v[98:99], 0, s[84:85]
	global_store_dword v[98:99], v100, off

.LBB0_407:
	v_or_b32_e32 v90, 32, v134
	v_ashrrev_i32_e32 v91, 31, v90
	v_mov_b32_e32 v99, v98
	v_lshlrev_b64 v[92:93], 12, v[90:91]
	v_cvt_pk_bf16_f32 v100, v100, v101
	v_cvt_pk_bf16_f32 v101, v96, v97
	v_cvt_pk_bf16_f32 v102, v102, v103
	v_cvt_pk_bf16_f32 v103, v94, v95
	v_mov_b32_e32 v94, v98
	v_mov_b32_e32 v95, v98
	v_lshl_add_u64 v[92:93], v[122:123], 0, v[92:93]
	v_pk_mul_f32 v[88:89], v[88:89], v[94:95]
	v_pk_mul_f32 v[86:87], v[86:87], v[98:99]
	v_pk_mul_f32 v[84:85], v[84:85], v[94:95]
	v_pk_mul_f32 v[82:83], v[82:83], v[98:99]
	s_and_b64 vcc, exec, s[44:45]
	s_mov_b64 s[26:27], -1
	global_store_dwordx4 v[92:93], v[100:103], off sc1
	s_cbranch_vccnz .LBB0_409
	s_mov_b64 s[26:27], 0

.LBB0_411:
	s_and_b64 vcc, exec, s[46:47]
	v_cvt_pk_bf16_f32 v86, v86, v87
	v_cvt_pk_bf16_f32 v87, v88, v89
	v_cvt_pk_bf16_f32 v88, v82, v83
	v_cvt_pk_bf16_f32 v89, v84, v85
	global_store_dwordx4 v[92:93], v[86:89], off offset:256 sc1
	s_cbranch_vccnz .LBB0_415
	v_and_b32_e32 v83, 64, v222
	v_xor_b32_e32 v82, 16, v222
	v_add_u32_e32 v83, 64, v83
	v_cmp_lt_i32_e32 vcc, v82, v83
	v_xor_b32_e32 v84, 32, v222
	s_nop 0
	v_cndmask_b32_e32 v82, v222, v82, vcc
	v_lshlrev_b32_e32 v82, 2, v82
	ds_bpermute_b32 v82, v82, v104
	v_cmp_lt_i32_e32 vcc, v84, v83
	s_waitcnt lgkmcnt(0)
	v_add_f32_e32 v82, v104, v82
	v_cndmask_b32_e32 v83, v222, v84, vcc
	v_lshlrev_b32_e32 v83, 2, v83
	ds_bpermute_b32 v83, v83, v82
	s_and_saveexec_b64 s[26:27], s[40:41]
	s_cbranch_execz .LBB0_414
	s_sub_i32 s48, s19, s17
	v_readlane_b32 s68, v252, 15
	s_waitcnt lgkmcnt(0)
	v_add_f32_e32 v84, v82, v83
	s_lshl_b32 s48, s48, 2
	v_lshlrev_b64 v[82:83], 7, v[90:91]
	v_readlane_b32 s69, v252, 16
	s_ashr_i32 s49, s48, 31
	s_lshl_b32 s84, s3, 2
	v_lshl_add_u64 v[82:83], s[68:69], 0, v[82:83]
	v_lshl_add_u64 v[82:83], s[48:49], 2, v[82:83]
	v_lshl_add_u64 v[82:83], v[82:83], 0, s[84:85]
	global_store_dword v[82:83], v84, off

.LBB0_419:
	v_or_b32_e32 v74, 48, v134
	v_ashrrev_i32_e32 v75, 31, v74
	v_mov_b32_e32 v83, v82
	v_lshlrev_b64 v[76:77], 12, v[74:75]
	v_cvt_pk_bf16_f32 v84, v84, v85
	v_cvt_pk_bf16_f32 v85, v80, v81
	v_cvt_pk_bf16_f32 v86, v86, v87
	v_cvt_pk_bf16_f32 v87, v78, v79
	v_mov_b32_e32 v78, v82
	v_mov_b32_e32 v79, v82
	v_lshl_add_u64 v[76:77], v[122:123], 0, v[76:77]
	v_pk_mul_f32 v[72:73], v[72:73], v[78:79]
	v_pk_mul_f32 v[70:71], v[70:71], v[82:83]
	v_pk_mul_f32 v[68:69], v[68:69], v[78:79]
	v_pk_mul_f32 v[66:67], v[66:67], v[82:83]
	s_and_b64 vcc, exec, s[44:45]
	s_mov_b64 s[26:27], -1
	global_store_dwordx4 v[76:77], v[84:87], off sc1
	s_cbranch_vccnz .LBB0_421
	s_mov_b64 s[26:27], 0

.LBB0_423:
	s_and_b64 vcc, exec, s[46:47]
	v_cvt_pk_bf16_f32 v70, v70, v71
	v_cvt_pk_bf16_f32 v71, v72, v73
	v_cvt_pk_bf16_f32 v72, v66, v67
	v_cvt_pk_bf16_f32 v73, v68, v69
	global_store_dwordx4 v[76:77], v[70:73], off offset:256 sc1
	s_cbranch_vccnz .LBB0_427
	v_and_b32_e32 v67, 64, v222
	v_xor_b32_e32 v66, 16, v222
	v_add_u32_e32 v67, 64, v67
	v_cmp_lt_i32_e32 vcc, v66, v67
	v_xor_b32_e32 v68, 32, v222
	s_nop 0
	v_cndmask_b32_e32 v66, v222, v66, vcc
	v_lshlrev_b32_e32 v66, 2, v66
	ds_bpermute_b32 v66, v66, v88
	v_cmp_lt_i32_e32 vcc, v68, v67
	s_waitcnt lgkmcnt(0)
	v_add_f32_e32 v66, v88, v66
	v_cndmask_b32_e32 v67, v222, v68, vcc
	v_lshlrev_b32_e32 v67, 2, v67
	ds_bpermute_b32 v67, v67, v66
	s_and_saveexec_b64 s[26:27], s[40:41]
	s_cbranch_execz .LBB0_426
	s_sub_i32 s48, s19, s17
	v_readlane_b32 s68, v252, 15
	s_waitcnt lgkmcnt(0)
	v_add_f32_e32 v68, v66, v67
	s_lshl_b32 s48, s48, 2
	v_lshlrev_b64 v[66:67], 7, v[74:75]
	v_readlane_b32 s69, v252, 16
	s_ashr_i32 s49, s48, 31
	s_lshl_b32 s84, s3, 2
	v_lshl_add_u64 v[66:67], s[68:69], 0, v[66:67]
	v_lshl_add_u64 v[66:67], s[48:49], 2, v[66:67]
	v_lshl_add_u64 v[66:67], v[66:67], 0, s[84:85]
	global_store_dword v[66:67], v68, off

.LBB0_431:
	v_add_u32_e32 v58, 0x80, v134
	v_ashrrev_i32_e32 v59, 31, v58
	v_mov_b32_e32 v67, v66
	v_lshlrev_b64 v[60:61], 12, v[58:59]
	v_cvt_pk_bf16_f32 v68, v68, v69
	v_cvt_pk_bf16_f32 v69, v64, v65
	v_cvt_pk_bf16_f32 v70, v70, v71
	v_cvt_pk_bf16_f32 v71, v62, v63
	v_mov_b32_e32 v62, v66
	v_mov_b32_e32 v63, v66
	v_lshl_add_u64 v[60:61], v[122:123], 0, v[60:61]
	v_pk_mul_f32 v[56:57], v[56:57], v[62:63]
	v_pk_mul_f32 v[54:55], v[54:55], v[66:67]
	v_pk_mul_f32 v[52:53], v[52:53], v[62:63]
	v_pk_mul_f32 v[50:51], v[50:51], v[66:67]
	s_and_b64 vcc, exec, s[44:45]
	s_mov_b64 s[26:27], -1
	global_store_dwordx4 v[60:61], v[68:71], off sc1
	s_cbranch_vccnz .LBB0_433
	s_mov_b64 s[26:27], 0

.LBB0_435:
	s_and_b64 vcc, exec, s[46:47]
	v_cvt_pk_bf16_f32 v54, v54, v55
	v_cvt_pk_bf16_f32 v55, v56, v57
	v_cvt_pk_bf16_f32 v56, v50, v51
	v_cvt_pk_bf16_f32 v57, v52, v53
	global_store_dwordx4 v[60:61], v[54:57], off offset:256 sc1
	s_cbranch_vccnz .LBB0_439
	v_and_b32_e32 v51, 64, v222
	v_xor_b32_e32 v50, 16, v222
	v_add_u32_e32 v51, 64, v51
	v_cmp_lt_i32_e32 vcc, v50, v51
	v_xor_b32_e32 v52, 32, v222
	s_nop 0
	v_cndmask_b32_e32 v50, v222, v50, vcc
	v_lshlrev_b32_e32 v50, 2, v50
	ds_bpermute_b32 v50, v50, v72
	v_cmp_lt_i32_e32 vcc, v52, v51
	s_waitcnt lgkmcnt(0)
	v_add_f32_e32 v50, v72, v50
	v_cndmask_b32_e32 v51, v222, v52, vcc
	v_lshlrev_b32_e32 v51, 2, v51
	ds_bpermute_b32 v51, v51, v50
	s_and_saveexec_b64 s[26:27], s[40:41]
	s_cbranch_execz .LBB0_438
	s_sub_i32 s48, s19, s17
	v_readlane_b32 s68, v252, 15
	s_waitcnt lgkmcnt(0)
	v_add_f32_e32 v52, v50, v51
	s_lshl_b32 s48, s48, 2
	v_lshlrev_b64 v[50:51], 7, v[58:59]
	v_readlane_b32 s69, v252, 16
	s_ashr_i32 s49, s48, 31
	s_lshl_b32 s84, s3, 2
	v_lshl_add_u64 v[50:51], s[68:69], 0, v[50:51]
	v_lshl_add_u64 v[50:51], s[48:49], 2, v[50:51]
	v_lshl_add_u64 v[50:51], v[50:51], 0, s[84:85]
	global_store_dword v[50:51], v52, off

.LBB0_443:
	v_add_u32_e32 v42, 0x90, v134
	v_ashrrev_i32_e32 v43, 31, v42
	v_mov_b32_e32 v51, v50
	v_lshlrev_b64 v[44:45], 12, v[42:43]
	v_cvt_pk_bf16_f32 v52, v52, v53
	v_cvt_pk_bf16_f32 v53, v48, v49
	v_cvt_pk_bf16_f32 v54, v54, v55
	v_cvt_pk_bf16_f32 v55, v46, v47
	v_mov_b32_e32 v46, v50
	v_mov_b32_e32 v47, v50
	v_lshl_add_u64 v[44:45], v[122:123], 0, v[44:45]
	v_pk_mul_f32 v[40:41], v[40:41], v[46:47]
	v_pk_mul_f32 v[38:39], v[38:39], v[50:51]
	v_pk_mul_f32 v[36:37], v[36:37], v[46:47]
	v_pk_mul_f32 v[34:35], v[34:35], v[50:51]
	s_and_b64 vcc, exec, s[44:45]
	s_mov_b64 s[26:27], -1
	global_store_dwordx4 v[44:45], v[52:55], off sc1
	s_cbranch_vccnz .LBB0_445
	s_mov_b64 s[26:27], 0

.LBB0_447:
	s_and_b64 vcc, exec, s[46:47]
	v_cvt_pk_bf16_f32 v38, v38, v39
	v_cvt_pk_bf16_f32 v39, v40, v41
	v_cvt_pk_bf16_f32 v40, v34, v35
	v_cvt_pk_bf16_f32 v41, v36, v37
	global_store_dwordx4 v[44:45], v[38:41], off offset:256 sc1
	s_cbranch_vccnz .LBB0_451
	v_and_b32_e32 v35, 64, v222
	v_xor_b32_e32 v34, 16, v222
	v_add_u32_e32 v35, 64, v35
	v_cmp_lt_i32_e32 vcc, v34, v35
	v_xor_b32_e32 v36, 32, v222
	s_nop 0
	v_cndmask_b32_e32 v34, v222, v34, vcc
	v_lshlrev_b32_e32 v34, 2, v34
	ds_bpermute_b32 v34, v34, v56
	v_cmp_lt_i32_e32 vcc, v36, v35
	s_waitcnt lgkmcnt(0)
	v_add_f32_e32 v34, v56, v34
	v_cndmask_b32_e32 v35, v222, v36, vcc
	v_lshlrev_b32_e32 v35, 2, v35
	ds_bpermute_b32 v35, v35, v34
	s_and_saveexec_b64 s[26:27], s[40:41]
	s_cbranch_execz .LBB0_450
	s_sub_i32 s48, s19, s17
	v_readlane_b32 s68, v252, 15
	s_waitcnt lgkmcnt(0)
	v_add_f32_e32 v36, v34, v35
	s_lshl_b32 s48, s48, 2
	v_lshlrev_b64 v[34:35], 7, v[42:43]
	v_readlane_b32 s69, v252, 16
	s_ashr_i32 s49, s48, 31
	s_lshl_b32 s84, s3, 2
	v_lshl_add_u64 v[34:35], s[68:69], 0, v[34:35]
	v_lshl_add_u64 v[34:35], s[48:49], 2, v[34:35]
	v_lshl_add_u64 v[34:35], v[34:35], 0, s[84:85]
	global_store_dword v[34:35], v36, off

.LBB0_455:
	v_add_u32_e32 v26, 0xa0, v134
	v_ashrrev_i32_e32 v27, 31, v26
	v_mov_b32_e32 v35, v34
	v_lshlrev_b64 v[28:29], 12, v[26:27]
	v_cvt_pk_bf16_f32 v36, v36, v37
	v_cvt_pk_bf16_f32 v37, v32, v33
	v_cvt_pk_bf16_f32 v38, v38, v39
	v_cvt_pk_bf16_f32 v39, v30, v31
	v_mov_b32_e32 v30, v34
	v_mov_b32_e32 v31, v34
	v_lshl_add_u64 v[28:29], v[122:123], 0, v[28:29]
	v_pk_mul_f32 v[24:25], v[24:25], v[30:31]
	v_pk_mul_f32 v[22:23], v[22:23], v[34:35]
	v_pk_mul_f32 v[20:21], v[20:21], v[30:31]
	v_pk_mul_f32 v[18:19], v[18:19], v[34:35]
	s_and_b64 vcc, exec, s[44:45]
	s_mov_b64 s[26:27], -1
	global_store_dwordx4 v[28:29], v[36:39], off sc1
	s_cbranch_vccnz .LBB0_457
	s_mov_b64 s[26:27], 0

.LBB0_459:
	s_and_b64 vcc, exec, s[46:47]
	v_cvt_pk_bf16_f32 v22, v22, v23
	v_cvt_pk_bf16_f32 v23, v24, v25
	v_cvt_pk_bf16_f32 v24, v18, v19
	v_cvt_pk_bf16_f32 v25, v20, v21
	global_store_dwordx4 v[28:29], v[22:25], off offset:256 sc1
	s_cbranch_vccnz .LBB0_463
	v_and_b32_e32 v19, 64, v222
	v_xor_b32_e32 v18, 16, v222
	v_add_u32_e32 v19, 64, v19
	v_cmp_lt_i32_e32 vcc, v18, v19
	v_xor_b32_e32 v20, 32, v222
	s_nop 0
	v_cndmask_b32_e32 v18, v222, v18, vcc
	v_lshlrev_b32_e32 v18, 2, v18
	ds_bpermute_b32 v18, v18, v40
	v_cmp_lt_i32_e32 vcc, v20, v19
	s_waitcnt lgkmcnt(0)
	v_add_f32_e32 v18, v40, v18
	v_cndmask_b32_e32 v19, v222, v20, vcc
	v_lshlrev_b32_e32 v19, 2, v19
	ds_bpermute_b32 v19, v19, v18
	s_and_saveexec_b64 s[26:27], s[40:41]
	s_cbranch_execz .LBB0_462
	s_sub_i32 s48, s19, s17
	v_readlane_b32 s68, v252, 15
	s_waitcnt lgkmcnt(0)
	v_add_f32_e32 v20, v18, v19
	s_lshl_b32 s48, s48, 2
	v_lshlrev_b64 v[18:19], 7, v[26:27]
	v_readlane_b32 s69, v252, 16
	s_ashr_i32 s49, s48, 31
	s_lshl_b32 s84, s3, 2
	v_lshl_add_u64 v[18:19], s[68:69], 0, v[18:19]
	v_lshl_add_u64 v[18:19], s[48:49], 2, v[18:19]
	v_lshl_add_u64 v[18:19], v[18:19], 0, s[84:85]
	global_store_dword v[18:19], v20, off

.LBB0_467:
	v_add_u32_e32 v10, 0xb0, v134
	v_ashrrev_i32_e32 v11, 31, v10
	v_mov_b32_e32 v19, v18
	v_lshlrev_b64 v[12:13], 12, v[10:11]
	v_cvt_pk_bf16_f32 v20, v20, v21
	v_cvt_pk_bf16_f32 v21, v16, v17
	v_cvt_pk_bf16_f32 v22, v22, v23
	v_cvt_pk_bf16_f32 v23, v14, v15
	v_mov_b32_e32 v14, v18
	v_mov_b32_e32 v15, v18
	v_lshl_add_u64 v[12:13], v[122:123], 0, v[12:13]
	v_pk_mul_f32 v[8:9], v[8:9], v[14:15]
	v_pk_mul_f32 v[6:7], v[6:7], v[18:19]
	v_pk_mul_f32 v[4:5], v[4:5], v[14:15]
	v_pk_mul_f32 v[2:3], v[2:3], v[18:19]
	s_and_b64 vcc, exec, s[44:45]
	s_mov_b64 s[26:27], -1
	global_store_dwordx4 v[12:13], v[20:23], off sc1
	s_cbranch_vccnz .LBB0_469
	s_mov_b64 s[26:27], 0

.LBB0_471:
	s_and_b64 vcc, exec, s[46:47]
	v_cvt_pk_bf16_f32 v6, v6, v7
	v_cvt_pk_bf16_f32 v7, v8, v9
	v_cvt_pk_bf16_f32 v8, v2, v3
	v_cvt_pk_bf16_f32 v9, v4, v5
	global_store_dwordx4 v[12:13], v[6:9], off offset:256 sc1
	s_cbranch_vccnz .LBB0_475
	v_and_b32_e32 v3, 64, v222
	v_xor_b32_e32 v2, 16, v222
	v_add_u32_e32 v3, 64, v3
	v_cmp_lt_i32_e32 vcc, v2, v3
	s_nop 1
	v_cndmask_b32_e32 v2, v222, v2, vcc
	v_lshlrev_b32_e32 v2, 2, v2
	ds_bpermute_b32 v2, v2, v0
	s_waitcnt lgkmcnt(0)
	v_add_f32_e32 v0, v0, v2
	v_xor_b32_e32 v2, 32, v222
	v_cmp_lt_i32_e32 vcc, v2, v3
	s_nop 1
	v_cndmask_b32_e32 v2, v222, v2, vcc
	v_lshlrev_b32_e32 v2, 2, v2
	ds_bpermute_b32 v2, v2, v0
	s_and_saveexec_b64 s[26:27], s[40:41]
	s_cbranch_execz .LBB0_474
	s_sub_i32 s19, s19, s17
	v_readlane_b32 s46, v252, 15
	s_waitcnt lgkmcnt(0)
	v_add_f32_e32 v0, v0, v2
	s_lshl_b32 s44, s19, 2
	v_lshlrev_b64 v[2:3], 7, v[10:11]
	v_readlane_b32 s47, v252, 16
	s_ashr_i32 s45, s44, 31
	s_lshl_b32 s84, s3, 2
	v_lshl_add_u64 v[2:3], s[46:47], 0, v[2:3]
	v_lshl_add_u64 v[2:3], s[44:45], 2, v[2:3]
	v_lshl_add_u64 v[2:3], v[2:3], 0, s[84:85]
	global_store_dword v[2:3], v0, off

.LBB0_496:
	v_lshl_or_b32 v146, s97, 8, v156
	v_ashrrev_i32_e32 v147, 31, v146
	v_lshl_add_u64 v[102:103], v[146:147], 2, s[86:87]
	global_load_dwordx4 v[106:109], v[102:103], off offset:16
	global_load_dwordx4 v[110:113], v[102:103], off
	global_load_dwordx4 v[98:101], v[102:103], off offset:528
	s_nop 0
	global_load_dwordx4 v[102:105], v[102:103], off offset:512
	v_lshl_add_u32 v150, s96, 8, v155
	v_ashrrev_i32_e32 v151, 31, v150
	v_readlane_b32 s26, v252, 39
	v_lshlrev_b64 v[148:149], 15, v[150:151]
	v_readlane_b32 s27, v252, 40
	v_readlane_b32 s90, v255, 12
	v_readlane_b32 s91, v255, 13
	v_lshl_add_u64 v[160:161], s[26:27], 0, v[148:149]
	v_lshlrev_b64 v[148:149], 1, v[146:147]
	v_lshl_add_u64 v[146:147], v[160:161], 0, v[148:149]
	s_waitcnt vmcnt(3)
	v_pk_mul_f32 v[160:161], v[140:141], v[108:109]
	s_waitcnt vmcnt(2)
	v_pk_mul_f32 v[144:145], v[144:145], v[112:113]
	v_pk_mul_f32 v[142:143], v[142:143], v[110:111]
	v_pk_mul_f32 v[140:141], v[138:139], v[106:107]
	v_cvt_pk_bf16_f32 v138, v142, v143
	v_cvt_pk_bf16_f32 v139, v144, v145
	s_waitcnt vmcnt(0)
	v_pk_mul_f32 v[134:135], v[134:135], v[102:103]
	v_cvt_pk_bf16_f32 v140, v140, v141
	v_cvt_pk_bf16_f32 v141, v160, v161
	global_store_dwordx4 v[146:147], v[138:141], off sc1
	v_pk_mul_f32 v[136:137], v[136:137], v[104:105]
	v_pk_mul_f32 v[128:129], v[128:129], v[112:113]
	v_pk_mul_f32 v[138:139], v[132:133], v[100:101]
	v_pk_mul_f32 v[132:133], v[130:131], v[98:99]
	v_cvt_pk_bf16_f32 v130, v134, v135
	v_cvt_pk_bf16_f32 v131, v136, v137
	v_pk_mul_f32 v[126:127], v[126:127], v[110:111]
	v_cvt_pk_bf16_f32 v132, v132, v133
	v_cvt_pk_bf16_f32 v133, v138, v139
	global_store_dwordx4 v[146:147], v[130:133], off offset:256 sc1
	v_pk_mul_f32 v[118:119], v[118:119], v[102:103]
	v_pk_mul_f32 v[120:121], v[120:121], v[104:105]
	v_or_b32_e32 v130, 16, v150
	v_ashrrev_i32_e32 v131, 31, v130
	v_lshlrev_b64 v[130:131], 15, v[130:131]
	v_lshl_add_u64 v[130:131], s[26:27], 0, v[130:131]
	v_lshl_add_u64 v[130:131], v[130:131], 0, v[148:149]
	v_pk_mul_f32 v[132:133], v[124:125], v[108:109]
	v_pk_mul_f32 v[124:125], v[122:123], v[106:107]
	v_cvt_pk_bf16_f32 v122, v126, v127
	v_cvt_pk_bf16_f32 v123, v128, v129
	v_pk_mul_f32 v[96:97], v[96:97], v[112:113]
	v_cvt_pk_bf16_f32 v124, v124, v125
	v_cvt_pk_bf16_f32 v125, v132, v133
	global_store_dwordx4 v[130:131], v[122:125], off sc1
	v_pk_mul_f32 v[94:95], v[94:95], v[110:111]
	v_pk_mul_f32 v[86:87], v[86:87], v[102:103]
	v_pk_mul_f32 v[122:123], v[116:117], v[100:101]
	v_pk_mul_f32 v[116:117], v[114:115], v[98:99]
	v_cvt_pk_bf16_f32 v114, v118, v119
	v_cvt_pk_bf16_f32 v115, v120, v121
	v_pk_mul_f32 v[88:89], v[88:89], v[104:105]
	v_cvt_pk_bf16_f32 v116, v116, v117
	v_cvt_pk_bf16_f32 v117, v122, v123
	global_store_dwordx4 v[130:131], v[114:117], off offset:256 sc1
	v_pk_mul_f32 v[80:81], v[80:81], v[112:113]
	v_pk_mul_f32 v[78:79], v[78:79], v[110:111]
	v_or_b32_e32 v114, 32, v150
	v_ashrrev_i32_e32 v115, 31, v114
	v_lshlrev_b64 v[114:115], 15, v[114:115]
	v_lshl_add_u64 v[114:115], s[26:27], 0, v[114:115]
	v_lshl_add_u64 v[114:115], v[114:115], 0, v[148:149]
	v_pk_mul_f32 v[116:117], v[92:93], v[108:109]
	v_pk_mul_f32 v[92:93], v[90:91], v[106:107]
	v_cvt_pk_bf16_f32 v90, v94, v95
	v_cvt_pk_bf16_f32 v91, v96, v97
	v_pk_mul_f32 v[72:73], v[72:73], v[104:105]
	v_cvt_pk_bf16_f32 v92, v92, v93
	v_cvt_pk_bf16_f32 v93, v116, v117
	global_store_dwordx4 v[114:115], v[90:93], off sc1
	v_pk_mul_f32 v[70:71], v[70:71], v[102:103]
	v_pk_mul_f32 v[62:63], v[62:63], v[110:111]
	v_pk_mul_f32 v[90:91], v[84:85], v[100:101]
	v_pk_mul_f32 v[84:85], v[82:83], v[98:99]
	v_cvt_pk_bf16_f32 v82, v86, v87
	v_cvt_pk_bf16_f32 v83, v88, v89
	v_pk_mul_f32 v[64:65], v[64:65], v[112:113]
	v_cvt_pk_bf16_f32 v84, v84, v85
	v_cvt_pk_bf16_f32 v85, v90, v91
	global_store_dwordx4 v[114:115], v[82:85], off offset:256 sc1
	v_pk_mul_f32 v[56:57], v[56:57], v[104:105]
	v_pk_mul_f32 v[54:55], v[54:55], v[102:103]
	v_or_b32_e32 v82, 48, v150
	v_ashrrev_i32_e32 v83, 31, v82
	v_lshlrev_b64 v[82:83], 15, v[82:83]
	v_lshl_add_u64 v[82:83], s[26:27], 0, v[82:83]
	v_lshl_add_u64 v[82:83], v[82:83], 0, v[148:149]
	v_pk_mul_f32 v[84:85], v[76:77], v[108:109]
	v_pk_mul_f32 v[76:77], v[74:75], v[106:107]
	v_cvt_pk_bf16_f32 v74, v78, v79
	v_cvt_pk_bf16_f32 v75, v80, v81
	s_mov_b64 s[26:27], 0x400000
	v_cvt_pk_bf16_f32 v76, v76, v77
	v_cvt_pk_bf16_f32 v77, v84, v85
	global_store_dwordx4 v[82:83], v[74:77], off sc1
	v_pk_mul_f32 v[50:51], v[50:51], v[110:111]
	v_pk_mul_f32 v[40:41], v[40:41], v[104:105]
	v_pk_mul_f32 v[74:75], v[68:69], v[100:101]
	v_pk_mul_f32 v[68:69], v[66:67], v[98:99]
	v_cvt_pk_bf16_f32 v66, v70, v71
	v_cvt_pk_bf16_f32 v67, v72, v73
	v_pk_mul_f32 v[38:39], v[38:39], v[102:103]
	v_cvt_pk_bf16_f32 v68, v68, v69
	v_cvt_pk_bf16_f32 v69, v74, v75
	global_store_dwordx4 v[82:83], v[66:69], off offset:256 sc1
	v_pk_mul_f32 v[34:35], v[34:35], v[110:111]
	v_pk_mul_f32 v[24:25], v[24:25], v[104:105]
	v_lshl_add_u64 v[66:67], v[146:147], 0, s[26:27]
	s_mov_b32 s26, 0x400000
	v_pk_mul_f32 v[68:69], v[60:61], v[108:109]
	v_pk_mul_f32 v[60:61], v[58:59], v[106:107]
	v_cvt_pk_bf16_f32 v58, v62, v63
	v_add_co_u32_e32 v62, vcc, s26, v146
	v_cvt_pk_bf16_f32 v59, v64, v65
	v_cvt_pk_bf16_f32 v60, v60, v61
	v_cvt_pk_bf16_f32 v61, v68, v69
	s_mov_b64 s[26:27], 0x480000
	s_nop 0
	v_addc_co_u32_e32 v63, vcc, 0, v147, vcc
	global_store_dwordx4 v[62:63], v[58:61], off sc1
	v_pk_mul_f32 v[22:23], v[22:23], v[102:103]
	v_pk_mul_f32 v[18:19], v[18:19], v[110:111]
	v_pk_mul_f32 v[58:59], v[48:49], v[100:101]
	v_pk_mul_f32 v[48:49], v[46:47], v[98:99]
	v_cvt_pk_bf16_f32 v46, v54, v55
	v_cvt_pk_bf16_f32 v47, v56, v57
	v_pk_mul_f32 v[8:9], v[8:9], v[104:105]
	v_cvt_pk_bf16_f32 v48, v48, v49
	v_cvt_pk_bf16_f32 v49, v58, v59
	global_store_dwordx4 v[66:67], v[46:49], off offset:256 sc1
	v_pk_mul_f32 v[6:7], v[6:7], v[102:103]
	s_nop 0
	v_lshl_add_u64 v[46:47], v[146:147], 0, s[26:27]
	v_pk_mul_f32 v[48:49], v[52:53], v[112:113]
	s_mov_b32 s26, 0x480000
	v_pk_mul_f32 v[52:53], v[44:45], v[108:109]
	v_pk_mul_f32 v[44:45], v[42:43], v[106:107]
	v_cvt_pk_bf16_f32 v42, v50, v51
	v_cvt_pk_bf16_f32 v43, v48, v49
	v_add_co_u32_e32 v48, vcc, s26, v146
	v_cvt_pk_bf16_f32 v44, v44, v45
	v_cvt_pk_bf16_f32 v45, v52, v53
	s_mov_b64 s[26:27], 0x500000
	s_nop 0
	v_addc_co_u32_e32 v49, vcc, 0, v147, vcc
	global_store_dwordx4 v[48:49], v[42:45], off sc1
	s_nop 1
	v_pk_mul_f32 v[42:43], v[32:33], v[100:101]
	v_pk_mul_f32 v[32:33], v[30:31], v[98:99]
	v_cvt_pk_bf16_f32 v30, v38, v39
	v_cvt_pk_bf16_f32 v31, v40, v41
	s_nop 0
	v_cvt_pk_bf16_f32 v32, v32, v33
	v_cvt_pk_bf16_f32 v33, v42, v43
	global_store_dwordx4 v[46:47], v[30:33], off offset:256 sc1
	s_nop 1
	v_lshl_add_u64 v[30:31], v[146:147], 0, s[26:27]
	v_pk_mul_f32 v[32:33], v[36:37], v[112:113]
	s_mov_b32 s26, 0x500000
	v_pk_mul_f32 v[36:37], v[28:29], v[108:109]
	v_pk_mul_f32 v[28:29], v[26:27], v[106:107]
	v_cvt_pk_bf16_f32 v26, v34, v35
	v_cvt_pk_bf16_f32 v27, v32, v33
	v_add_co_u32_e32 v32, vcc, s26, v146
	v_cvt_pk_bf16_f32 v28, v28, v29
	v_cvt_pk_bf16_f32 v29, v36, v37
	s_mov_b64 s[26:27], 0x580000
	s_nop 0
	v_addc_co_u32_e32 v33, vcc, 0, v147, vcc
	global_store_dwordx4 v[32:33], v[26:29], off sc1
	s_nop 1
	v_pk_mul_f32 v[26:27], v[16:17], v[100:101]
	v_pk_mul_f32 v[16:17], v[14:15], v[98:99]
	v_cvt_pk_bf16_f32 v14, v22, v23
	v_cvt_pk_bf16_f32 v15, v24, v25
	s_nop 0
	v_cvt_pk_bf16_f32 v16, v16, v17
	v_cvt_pk_bf16_f32 v17, v26, v27
	global_store_dwordx4 v[30:31], v[14:17], off offset:256 sc1
	s_nop 1
	v_lshl_add_u64 v[14:15], v[146:147], 0, s[26:27]
	v_pk_mul_f32 v[16:17], v[20:21], v[112:113]
	s_mov_b32 s26, 0x580000
	v_pk_mul_f32 v[20:21], v[12:13], v[108:109]
	v_pk_mul_f32 v[12:13], v[10:11], v[106:107]
	v_cvt_pk_bf16_f32 v10, v18, v19
	v_cvt_pk_bf16_f32 v11, v16, v17
	v_add_co_u32_e32 v16, vcc, s26, v146
	v_cvt_pk_bf16_f32 v12, v12, v13
	v_cvt_pk_bf16_f32 v13, v20, v21
	s_mov_b64 s[26:27], -1
	s_nop 0
	v_addc_co_u32_e32 v17, vcc, 0, v147, vcc
	global_store_dwordx4 v[16:17], v[10:13], off sc1
	s_andn2_b64 vcc, exec, s[40:41]
	s_nop 0
	v_pk_mul_f32 v[10:11], v[4:5], v[100:101]
	v_pk_mul_f32 v[4:5], v[2:3], v[98:99]
	v_cvt_pk_bf16_f32 v2, v6, v7
	v_cvt_pk_bf16_f32 v3, v8, v9
	s_nop 0
	v_cvt_pk_bf16_f32 v4, v4, v5
	v_cvt_pk_bf16_f32 v5, v10, v11
	global_store_dwordx4 v[14:15], v[2:5], off offset:256 sc1
	s_cbranch_vccnz .LBB0_485
	s_andn2_b64 vcc, exec, s[38:39]
	s_cbranch_vccnz .LBB0_484
	s_barrier
	s_branch .LBB0_484
